# previous best with the two back-to-back waits at the end of each K-loop load segment merged into one s_waitcnt vmcnt(8) lgkmcnt(0)
# baseline (speedup 1.0000x reference)
.LBB0_1790:
	ds_read_b128 v[146:149], v159
	ds_read_b128 v[150:153], v159 offset:1024
	ds_read_b128 v[164:167], v159 offset:2048
	ds_read_b128 v[168:171], v159 offset:3072
	ds_read_b128 v[172:175], v160
	ds_read_b128 v[176:179], v160 offset:1024
	ds_read_b128 v[186:189], v160 offset:2048
	ds_read_b128 v[190:193], v160 offset:3072
	s_add_u32 s79, s6, 0xfff00080
	s_addc_u32 s80, s7, -1
	s_cmp_eq_u32 s78, 60
	s_cselect_b32 s91, s45, s80
	s_cselect_b32 s90, s74, s79
	s_cselect_b32 s89, s43, s77
	s_cselect_b32 s88, s75, s76
	s_add_i32 m0, s33, 0xc000
	ds_read_b128 v[194:197], v161
	ds_read_b128 v[198:201], v161 offset:1024
	ds_read_b128 v[202:205], v161 offset:2048
	ds_read_b128 v[206:209], v161 offset:3072
	ds_read_b128 v[210:213], v161 offset:4096
	ds_read_b128 v[214:217], v161 offset:5120
	ds_read_b128 v[218:221], v161 offset:6144
	ds_read_b128 v[222:225], v161 offset:7168
	global_load_lds_dwordx4 v138, s[6:7]
	s_add_i32 m0, s33, 0xe000
	s_nop 0
	global_load_lds_dwordx4 v140, s[6:7]
	s_waitcnt vmcnt(8) lgkmcnt(0)
	s_barrier
	v_mfma_f32_16x16x32_bf16 v[126:129], v[146:149], v[194:197], v[126:129]
	v_mfma_f32_16x16x32_bf16 v[126:129], v[150:153], v[198:201], v[126:129]
	v_mfma_f32_16x16x32_bf16 v[122:125], v[164:167], v[194:197], v[122:125]
	v_mfma_f32_16x16x32_bf16 v[122:125], v[168:171], v[198:201], v[122:125]
	v_mfma_f32_16x16x32_bf16 v[118:121], v[172:175], v[194:197], v[118:121]
	v_mfma_f32_16x16x32_bf16 v[118:121], v[176:179], v[198:201], v[118:121]
	v_mfma_f32_16x16x32_bf16 v[110:113], v[186:189], v[194:197], v[110:113]
	v_mfma_f32_16x16x32_bf16 v[110:113], v[190:193], v[198:201], v[110:113]
	v_mfma_f32_16x16x32_bf16 v[114:117], v[146:149], v[202:205], v[114:117]
	v_mfma_f32_16x16x32_bf16 v[114:117], v[150:153], v[206:209], v[114:117]
	v_mfma_f32_16x16x32_bf16 v[106:109], v[164:167], v[202:205], v[106:109]
	v_mfma_f32_16x16x32_bf16 v[106:109], v[168:171], v[206:209], v[106:109]
	v_mfma_f32_16x16x32_bf16 v[102:105], v[172:175], v[202:205], v[102:105]
	v_mfma_f32_16x16x32_bf16 v[102:105], v[176:179], v[206:209], v[102:105]
	v_mfma_f32_16x16x32_bf16 v[94:97], v[186:189], v[202:205], v[94:97]
	v_mfma_f32_16x16x32_bf16 v[94:97], v[190:193], v[206:209], v[94:97]
	v_mfma_f32_16x16x32_bf16 v[98:101], v[146:149], v[210:213], v[98:101]
	v_mfma_f32_16x16x32_bf16 v[98:101], v[150:153], v[214:217], v[98:101]
	v_mfma_f32_16x16x32_bf16 v[90:93], v[164:167], v[210:213], v[90:93]
	v_mfma_f32_16x16x32_bf16 v[90:93], v[168:171], v[214:217], v[90:93]
	v_mfma_f32_16x16x32_bf16 v[86:89], v[172:175], v[210:213], v[86:89]
	v_mfma_f32_16x16x32_bf16 v[86:89], v[176:179], v[214:217], v[86:89]
	v_mfma_f32_16x16x32_bf16 v[78:81], v[186:189], v[210:213], v[78:81]
	v_mfma_f32_16x16x32_bf16 v[78:81], v[190:193], v[214:217], v[78:81]
	v_mfma_f32_16x16x32_bf16 v[82:85], v[146:149], v[218:221], v[82:85]
	v_mfma_f32_16x16x32_bf16 v[82:85], v[150:153], v[222:225], v[82:85]
	v_mfma_f32_16x16x32_bf16 v[74:77], v[164:167], v[218:221], v[74:77]
	v_mfma_f32_16x16x32_bf16 v[74:77], v[168:171], v[222:225], v[74:77]
	v_mfma_f32_16x16x32_bf16 v[70:73], v[172:175], v[218:221], v[70:73]
	v_mfma_f32_16x16x32_bf16 v[70:73], v[176:179], v[222:225], v[70:73]
	v_mfma_f32_16x16x32_bf16 v[66:69], v[186:189], v[218:221], v[66:69]
	v_mfma_f32_16x16x32_bf16 v[66:69], v[190:193], v[222:225], v[66:69]
	s_barrier
	s_add_i32 s79, s69, s25
	s_add_u32 s98, s88, 0x80
	s_addc_u32 s99, s89, 0
	s_mov_b32 m0, s79
	ds_read_b128 v[194:197], v161 offset:16384
	ds_read_b128 v[198:201], v161 offset:17408
	ds_read_b128 v[202:205], v161 offset:18432
	ds_read_b128 v[206:209], v161 offset:19456
	ds_read_b128 v[210:213], v161 offset:20480
	ds_read_b128 v[214:217], v161 offset:21504
	ds_read_b128 v[218:221], v161 offset:22528
	ds_read_b128 v[222:225], v161 offset:23552
	global_load_lds_dwordx4 v132, s[88:89]
	s_add_i32 m0, s79, 0x2000
	s_add_u32 s80, s88, 0x100000
	s_addc_u32 s81, s89, 0
	s_add_i32 s79, s70, s25
	global_load_lds_dwordx4 v136, s[88:89]
	s_mov_b32 m0, s79
	global_load_lds_dwordx4 v132, s[80:81]
	s_add_i32 m0, s79, 0x2000
	s_nop 0
	global_load_lds_dwordx4 v136, s[80:81]
	s_add_u32 s100, s90, 0x80
	s_addc_u32 s101, s91, 0
	s_mov_b32 m0, s33
	s_nop 0
	global_load_lds_dwordx4 v130, s[90:91]
	s_mov_b32 m0, s35
	s_nop 0
	global_load_lds_dwordx4 v134, s[90:91]
	s_waitcnt vmcnt(8) lgkmcnt(0)
	s_barrier
	v_mfma_f32_16x16x32_bf16 v[62:65], v[146:149], v[194:197], v[62:65]
	v_mfma_f32_16x16x32_bf16 v[62:65], v[150:153], v[198:201], v[62:65]
	v_mfma_f32_16x16x32_bf16 v[58:61], v[164:167], v[194:197], v[58:61]
	v_mfma_f32_16x16x32_bf16 v[58:61], v[168:171], v[198:201], v[58:61]
	v_mfma_f32_16x16x32_bf16 v[54:57], v[172:175], v[194:197], v[54:57]
	v_mfma_f32_16x16x32_bf16 v[54:57], v[176:179], v[198:201], v[54:57]
	v_mfma_f32_16x16x32_bf16 v[46:49], v[186:189], v[194:197], v[46:49]
	v_mfma_f32_16x16x32_bf16 v[46:49], v[190:193], v[198:201], v[46:49]
	v_mfma_f32_16x16x32_bf16 v[50:53], v[146:149], v[202:205], v[50:53]
	v_mfma_f32_16x16x32_bf16 v[50:53], v[150:153], v[206:209], v[50:53]
	v_mfma_f32_16x16x32_bf16 v[42:45], v[164:167], v[202:205], v[42:45]
	v_mfma_f32_16x16x32_bf16 v[42:45], v[168:171], v[206:209], v[42:45]
	v_mfma_f32_16x16x32_bf16 v[38:41], v[172:175], v[202:205], v[38:41]
	v_mfma_f32_16x16x32_bf16 v[38:41], v[176:179], v[206:209], v[38:41]
	v_mfma_f32_16x16x32_bf16 v[30:33], v[186:189], v[202:205], v[30:33]
	v_mfma_f32_16x16x32_bf16 v[30:33], v[190:193], v[206:209], v[30:33]
	v_mfma_f32_16x16x32_bf16 v[34:37], v[146:149], v[210:213], v[34:37]
	v_mfma_f32_16x16x32_bf16 v[34:37], v[150:153], v[214:217], v[34:37]
	v_mfma_f32_16x16x32_bf16 v[26:29], v[164:167], v[210:213], v[26:29]
	v_mfma_f32_16x16x32_bf16 v[26:29], v[168:171], v[214:217], v[26:29]
	v_mfma_f32_16x16x32_bf16 v[22:25], v[172:175], v[210:213], v[22:25]
	v_mfma_f32_16x16x32_bf16 v[22:25], v[176:179], v[214:217], v[22:25]
	v_mfma_f32_16x16x32_bf16 v[14:17], v[186:189], v[210:213], v[14:17]
	v_mfma_f32_16x16x32_bf16 v[14:17], v[190:193], v[214:217], v[14:17]
	v_mfma_f32_16x16x32_bf16 v[18:21], v[146:149], v[218:221], v[18:21]
	v_mfma_f32_16x16x32_bf16 v[18:21], v[150:153], v[222:225], v[18:21]
	v_mfma_f32_16x16x32_bf16 v[10:13], v[164:167], v[218:221], v[10:13]
	v_mfma_f32_16x16x32_bf16 v[10:13], v[168:171], v[222:225], v[10:13]
	v_mfma_f32_16x16x32_bf16 v[6:9], v[172:175], v[218:221], v[6:9]
	v_mfma_f32_16x16x32_bf16 v[6:9], v[176:179], v[222:225], v[6:9]
	v_mfma_f32_16x16x32_bf16 v[2:5], v[186:189], v[218:221], v[2:5]
	v_mfma_f32_16x16x32_bf16 v[2:5], v[190:193], v[222:225], v[2:5]
	s_barrier
	s_add_i32 s79, 0, 0x18000
	s_add_i32 s82, 0, 0x1c000
	ds_read_b128 v[146:149], v246
	ds_read_b128 v[150:153], v246 offset:1024
	ds_read_b128 v[164:167], v246 offset:2048
	ds_read_b128 v[168:171], v246 offset:3072
	ds_read_b128 v[172:175], v247
	ds_read_b128 v[176:179], v247 offset:1024
	ds_read_b128 v[186:189], v247 offset:2048
	ds_read_b128 v[190:193], v247 offset:3072
	s_add_u32 s80, s90, 0x100000
	s_addc_u32 s81, s91, 0
	s_mov_b32 m0, s59
	ds_read_b128 v[194:197], v161 offset:32768
	ds_read_b128 v[198:201], v161 offset:33792
	ds_read_b128 v[202:205], v161 offset:34816
	ds_read_b128 v[206:209], v161 offset:35840
	ds_read_b128 v[210:213], v161 offset:36864
	ds_read_b128 v[214:217], v161 offset:37888
	ds_read_b128 v[218:221], v161 offset:38912
	ds_read_b128 v[222:225], v161 offset:39936
	global_load_lds_dwordx4 v130, s[80:81]
	s_mov_b32 m0, s62
	s_nop 0
	global_load_lds_dwordx4 v134, s[80:81]
	s_waitcnt vmcnt(8) lgkmcnt(0)
	s_barrier
	v_mfma_f32_16x16x32_bf16 v[126:129], v[146:149], v[194:197], v[126:129]
	v_mfma_f32_16x16x32_bf16 v[126:129], v[150:153], v[198:201], v[126:129]
	v_mfma_f32_16x16x32_bf16 v[122:125], v[164:167], v[194:197], v[122:125]
	v_mfma_f32_16x16x32_bf16 v[122:125], v[168:171], v[198:201], v[122:125]
	v_mfma_f32_16x16x32_bf16 v[118:121], v[172:175], v[194:197], v[118:121]
	v_mfma_f32_16x16x32_bf16 v[118:121], v[176:179], v[198:201], v[118:121]
	v_mfma_f32_16x16x32_bf16 v[110:113], v[186:189], v[194:197], v[110:113]
	v_mfma_f32_16x16x32_bf16 v[110:113], v[190:193], v[198:201], v[110:113]
	v_mfma_f32_16x16x32_bf16 v[114:117], v[146:149], v[202:205], v[114:117]
	v_mfma_f32_16x16x32_bf16 v[114:117], v[150:153], v[206:209], v[114:117]
	v_mfma_f32_16x16x32_bf16 v[106:109], v[164:167], v[202:205], v[106:109]
	v_mfma_f32_16x16x32_bf16 v[106:109], v[168:171], v[206:209], v[106:109]
	v_mfma_f32_16x16x32_bf16 v[102:105], v[172:175], v[202:205], v[102:105]
	v_mfma_f32_16x16x32_bf16 v[102:105], v[176:179], v[206:209], v[102:105]
	v_mfma_f32_16x16x32_bf16 v[94:97], v[186:189], v[202:205], v[94:97]
	v_mfma_f32_16x16x32_bf16 v[94:97], v[190:193], v[206:209], v[94:97]
	v_mfma_f32_16x16x32_bf16 v[98:101], v[146:149], v[210:213], v[98:101]
	v_mfma_f32_16x16x32_bf16 v[98:101], v[150:153], v[214:217], v[98:101]
	v_mfma_f32_16x16x32_bf16 v[90:93], v[164:167], v[210:213], v[90:93]
	v_mfma_f32_16x16x32_bf16 v[90:93], v[168:171], v[214:217], v[90:93]
	v_mfma_f32_16x16x32_bf16 v[86:89], v[172:175], v[210:213], v[86:89]
	v_mfma_f32_16x16x32_bf16 v[86:89], v[176:179], v[214:217], v[86:89]
	v_mfma_f32_16x16x32_bf16 v[78:81], v[186:189], v[210:213], v[78:81]
	v_mfma_f32_16x16x32_bf16 v[78:81], v[190:193], v[214:217], v[78:81]
	v_mfma_f32_16x16x32_bf16 v[82:85], v[146:149], v[218:221], v[82:85]
	v_mfma_f32_16x16x32_bf16 v[82:85], v[150:153], v[222:225], v[82:85]
	v_mfma_f32_16x16x32_bf16 v[74:77], v[164:167], v[218:221], v[74:77]
	v_mfma_f32_16x16x32_bf16 v[74:77], v[168:171], v[222:225], v[74:77]
	v_mfma_f32_16x16x32_bf16 v[70:73], v[172:175], v[218:221], v[70:73]
	v_mfma_f32_16x16x32_bf16 v[70:73], v[176:179], v[222:225], v[70:73]
	v_mfma_f32_16x16x32_bf16 v[66:69], v[186:189], v[218:221], v[66:69]
	v_mfma_f32_16x16x32_bf16 v[66:69], v[190:193], v[222:225], v[66:69]
	s_barrier
	s_add_i32 s79, s79, s25
	s_mov_b32 m0, s79
	ds_read_b128 v[194:197], v161 offset:49152
	ds_read_b128 v[198:201], v161 offset:50176
	ds_read_b128 v[202:205], v161 offset:51200
	ds_read_b128 v[206:209], v161 offset:52224
	ds_read_b128 v[210:213], v161 offset:53248
	ds_read_b128 v[214:217], v161 offset:54272
	ds_read_b128 v[218:221], v161 offset:55296
	ds_read_b128 v[222:225], v161 offset:56320
	global_load_lds_dwordx4 v132, s[98:99]
	s_add_i32 m0, s79, 0x2000
	s_add_u32 s80, s88, 0x100080
	s_addc_u32 s81, s89, 0
	s_add_i32 s79, s82, s25
	global_load_lds_dwordx4 v136, s[98:99]
	s_mov_b32 m0, s79
	s_nop 0
	global_load_lds_dwordx4 v132, s[80:81]
	s_add_i32 m0, s79, 0x2000
	s_nop 0
	global_load_lds_dwordx4 v136, s[80:81]
	s_mov_b32 m0, s66
	s_nop 0
	global_load_lds_dwordx4 v130, s[100:101]
	s_mov_b32 m0, s67
	s_nop 0
	global_load_lds_dwordx4 v134, s[100:101]
	s_waitcnt vmcnt(8) lgkmcnt(0)
	s_barrier
	v_mfma_f32_16x16x32_bf16 v[62:65], v[146:149], v[194:197], v[62:65]
	v_mfma_f32_16x16x32_bf16 v[62:65], v[150:153], v[198:201], v[62:65]
	v_mfma_f32_16x16x32_bf16 v[58:61], v[164:167], v[194:197], v[58:61]
	v_mfma_f32_16x16x32_bf16 v[58:61], v[168:171], v[198:201], v[58:61]
	v_mfma_f32_16x16x32_bf16 v[54:57], v[172:175], v[194:197], v[54:57]
	v_mfma_f32_16x16x32_bf16 v[54:57], v[176:179], v[198:201], v[54:57]
	v_mfma_f32_16x16x32_bf16 v[46:49], v[186:189], v[194:197], v[46:49]
	v_mfma_f32_16x16x32_bf16 v[46:49], v[190:193], v[198:201], v[46:49]
	v_mfma_f32_16x16x32_bf16 v[50:53], v[146:149], v[202:205], v[50:53]
	v_mfma_f32_16x16x32_bf16 v[50:53], v[150:153], v[206:209], v[50:53]
	v_mfma_f32_16x16x32_bf16 v[42:45], v[164:167], v[202:205], v[42:45]
	v_mfma_f32_16x16x32_bf16 v[42:45], v[168:171], v[206:209], v[42:45]
	v_mfma_f32_16x16x32_bf16 v[38:41], v[172:175], v[202:205], v[38:41]
	v_mfma_f32_16x16x32_bf16 v[38:41], v[176:179], v[206:209], v[38:41]
	v_mfma_f32_16x16x32_bf16 v[30:33], v[186:189], v[202:205], v[30:33]
	v_mfma_f32_16x16x32_bf16 v[30:33], v[190:193], v[206:209], v[30:33]
	v_mfma_f32_16x16x32_bf16 v[34:37], v[146:149], v[210:213], v[34:37]
	v_mfma_f32_16x16x32_bf16 v[34:37], v[150:153], v[214:217], v[34:37]
	v_mfma_f32_16x16x32_bf16 v[26:29], v[164:167], v[210:213], v[26:29]
	v_mfma_f32_16x16x32_bf16 v[26:29], v[168:171], v[214:217], v[26:29]
	v_mfma_f32_16x16x32_bf16 v[22:25], v[172:175], v[210:213], v[22:25]
	v_mfma_f32_16x16x32_bf16 v[22:25], v[176:179], v[214:217], v[22:25]
	v_mfma_f32_16x16x32_bf16 v[14:17], v[186:189], v[210:213], v[14:17]
	v_mfma_f32_16x16x32_bf16 v[14:17], v[190:193], v[214:217], v[14:17]
	v_mfma_f32_16x16x32_bf16 v[18:21], v[146:149], v[218:221], v[18:21]
	v_mfma_f32_16x16x32_bf16 v[18:21], v[150:153], v[222:225], v[18:21]
	v_mfma_f32_16x16x32_bf16 v[10:13], v[164:167], v[218:221], v[10:13]
	v_mfma_f32_16x16x32_bf16 v[10:13], v[168:171], v[222:225], v[10:13]
	v_mfma_f32_16x16x32_bf16 v[6:9], v[172:175], v[218:221], v[6:9]
	v_mfma_f32_16x16x32_bf16 v[6:9], v[176:179], v[222:225], v[6:9]
	v_mfma_f32_16x16x32_bf16 v[2:5], v[186:189], v[218:221], v[2:5]
	v_mfma_f32_16x16x32_bf16 v[2:5], v[190:193], v[222:225], v[2:5]
	s_barrier
	s_add_i32 s78, s78, 2
	s_add_u32 s6, s6, 0x100
	s_addc_u32 s7, s7, 0
	s_add_u32 s76, s76, 0x100
	s_addc_u32 s77, s77, 0
	s_cmp_gt_u32 s78, 61
	s_cbranch_scc0 .LBB0_1790
	s_setprio 0
	s_and_b64 vcc, exec, s[40:41]
	s_cbranch_vccz .LBB0_1793
	s_barrier

.LBB0_2109:
	ds_read_b128 v[130:133], v155
	ds_read_b128 v[134:137], v155 offset:1024
	ds_read_b128 v[138:141], v155 offset:2048
	ds_read_b128 v[142:145], v155 offset:3072
	ds_read_b128 v[166:169], v176
	ds_read_b128 v[170:173], v176 offset:1024
	ds_read_b128 v[186:189], v176 offset:2048
	ds_read_b128 v[190:193], v176 offset:3072
	s_add_u32 s74, s50, 0xfff00080
	s_addc_u32 s75, s51, -1
	s_cmp_eq_u32 s73, 60
	s_cselect_b32 s85, s26, s75
	s_cselect_b32 s84, s45, s74
	s_cselect_b32 s83, s43, s72
	s_cselect_b32 s82, s70, s71
	s_add_i32 m0, s23, 0xc000
	ds_read_b128 v[194:197], v177
	ds_read_b128 v[198:201], v177 offset:1024
	ds_read_b128 v[202:205], v177 offset:2048
	ds_read_b128 v[206:209], v177 offset:3072
	ds_read_b128 v[210:213], v177 offset:4096
	ds_read_b128 v[214:217], v177 offset:5120
	ds_read_b128 v[218:221], v177 offset:6144
	ds_read_b128 v[222:225], v177 offset:7168
	global_load_lds_dwordx4 v158, s[50:51]
	s_add_i32 m0, s23, 0xe000
	s_nop 0
	global_load_lds_dwordx4 v160, s[50:51]
	s_waitcnt vmcnt(8) lgkmcnt(0)
	s_barrier
	v_mfma_f32_16x16x32_bf16 v[126:129], v[130:133], v[194:197], v[126:129]
	v_mfma_f32_16x16x32_bf16 v[126:129], v[134:137], v[198:201], v[126:129]
	v_mfma_f32_16x16x32_bf16 v[122:125], v[138:141], v[194:197], v[122:125]
	v_mfma_f32_16x16x32_bf16 v[122:125], v[142:145], v[198:201], v[122:125]
	v_mfma_f32_16x16x32_bf16 v[118:121], v[166:169], v[194:197], v[118:121]
	v_mfma_f32_16x16x32_bf16 v[118:121], v[170:173], v[198:201], v[118:121]
	v_mfma_f32_16x16x32_bf16 v[114:117], v[186:189], v[194:197], v[114:117]
	v_mfma_f32_16x16x32_bf16 v[114:117], v[190:193], v[198:201], v[114:117]
	v_mfma_f32_16x16x32_bf16 v[110:113], v[130:133], v[202:205], v[110:113]
	v_mfma_f32_16x16x32_bf16 v[110:113], v[134:137], v[206:209], v[110:113]
	v_mfma_f32_16x16x32_bf16 v[106:109], v[138:141], v[202:205], v[106:109]
	v_mfma_f32_16x16x32_bf16 v[106:109], v[142:145], v[206:209], v[106:109]
	v_mfma_f32_16x16x32_bf16 v[102:105], v[166:169], v[202:205], v[102:105]
	v_mfma_f32_16x16x32_bf16 v[102:105], v[170:173], v[206:209], v[102:105]
	v_mfma_f32_16x16x32_bf16 v[98:101], v[186:189], v[202:205], v[98:101]
	v_mfma_f32_16x16x32_bf16 v[98:101], v[190:193], v[206:209], v[98:101]
	v_mfma_f32_16x16x32_bf16 v[94:97], v[130:133], v[210:213], v[94:97]
	v_mfma_f32_16x16x32_bf16 v[94:97], v[134:137], v[214:217], v[94:97]
	v_mfma_f32_16x16x32_bf16 v[90:93], v[138:141], v[210:213], v[90:93]
	v_mfma_f32_16x16x32_bf16 v[90:93], v[142:145], v[214:217], v[90:93]
	v_mfma_f32_16x16x32_bf16 v[86:89], v[166:169], v[210:213], v[86:89]
	v_mfma_f32_16x16x32_bf16 v[86:89], v[170:173], v[214:217], v[86:89]
	v_mfma_f32_16x16x32_bf16 v[82:85], v[186:189], v[210:213], v[82:85]
	v_mfma_f32_16x16x32_bf16 v[82:85], v[190:193], v[214:217], v[82:85]
	v_mfma_f32_16x16x32_bf16 v[78:81], v[130:133], v[218:221], v[78:81]
	v_mfma_f32_16x16x32_bf16 v[78:81], v[134:137], v[222:225], v[78:81]
	v_mfma_f32_16x16x32_bf16 v[74:77], v[138:141], v[218:221], v[74:77]
	v_mfma_f32_16x16x32_bf16 v[74:77], v[142:145], v[222:225], v[74:77]
	v_mfma_f32_16x16x32_bf16 v[70:73], v[166:169], v[218:221], v[70:73]
	v_mfma_f32_16x16x32_bf16 v[70:73], v[170:173], v[222:225], v[70:73]
	v_mfma_f32_16x16x32_bf16 v[66:69], v[186:189], v[218:221], v[66:69]
	v_mfma_f32_16x16x32_bf16 v[66:69], v[190:193], v[222:225], v[66:69]
	s_barrier
	s_add_i32 s74, s67, s3
	s_add_u32 s98, s82, 0x80
	s_addc_u32 s99, s83, 0
	s_mov_b32 m0, s74
	ds_read_b128 v[194:197], v177 offset:16384
	ds_read_b128 v[198:201], v177 offset:17408
	ds_read_b128 v[202:205], v177 offset:18432
	ds_read_b128 v[206:209], v177 offset:19456
	ds_read_b128 v[210:213], v177 offset:20480
	ds_read_b128 v[214:217], v177 offset:21504
	ds_read_b128 v[218:221], v177 offset:22528
	ds_read_b128 v[222:225], v177 offset:23552
	global_load_lds_dwordx4 v148, s[82:83]
	s_add_i32 m0, s74, 0x2000
	s_add_u32 s74, s82, 0x100000
	s_addc_u32 s75, s83, 0
	s_add_i32 s76, s68, s3
	global_load_lds_dwordx4 v152, s[82:83]
	s_mov_b32 m0, s76
	global_load_lds_dwordx4 v148, s[74:75]
	s_add_i32 m0, s76, 0x2000
	s_nop 0
	global_load_lds_dwordx4 v152, s[74:75]
	s_add_u32 s100, s84, 0x80
	s_addc_u32 s101, s85, 0
	s_mov_b32 m0, s23
	s_nop 0
	global_load_lds_dwordx4 v146, s[84:85]
	s_mov_b32 m0, s25
	s_nop 0
	global_load_lds_dwordx4 v150, s[84:85]
	s_waitcnt vmcnt(8) lgkmcnt(0)
	s_barrier
	v_mfma_f32_16x16x32_bf16 v[62:65], v[130:133], v[194:197], v[62:65]
	v_mfma_f32_16x16x32_bf16 v[62:65], v[134:137], v[198:201], v[62:65]
	v_mfma_f32_16x16x32_bf16 v[58:61], v[138:141], v[194:197], v[58:61]
	v_mfma_f32_16x16x32_bf16 v[58:61], v[142:145], v[198:201], v[58:61]
	v_mfma_f32_16x16x32_bf16 v[54:57], v[166:169], v[194:197], v[54:57]
	v_mfma_f32_16x16x32_bf16 v[54:57], v[170:173], v[198:201], v[54:57]
	v_mfma_f32_16x16x32_bf16 v[50:53], v[186:189], v[194:197], v[50:53]
	v_mfma_f32_16x16x32_bf16 v[50:53], v[190:193], v[198:201], v[50:53]
	v_mfma_f32_16x16x32_bf16 v[46:49], v[130:133], v[202:205], v[46:49]
	v_mfma_f32_16x16x32_bf16 v[46:49], v[134:137], v[206:209], v[46:49]
	v_mfma_f32_16x16x32_bf16 v[42:45], v[138:141], v[202:205], v[42:45]
	v_mfma_f32_16x16x32_bf16 v[42:45], v[142:145], v[206:209], v[42:45]
	v_mfma_f32_16x16x32_bf16 v[38:41], v[166:169], v[202:205], v[38:41]
	v_mfma_f32_16x16x32_bf16 v[38:41], v[170:173], v[206:209], v[38:41]
	v_mfma_f32_16x16x32_bf16 v[34:37], v[186:189], v[202:205], v[34:37]
	v_mfma_f32_16x16x32_bf16 v[34:37], v[190:193], v[206:209], v[34:37]
	v_mfma_f32_16x16x32_bf16 v[30:33], v[130:133], v[210:213], v[30:33]
	v_mfma_f32_16x16x32_bf16 v[30:33], v[134:137], v[214:217], v[30:33]
	v_mfma_f32_16x16x32_bf16 v[26:29], v[138:141], v[210:213], v[26:29]
	v_mfma_f32_16x16x32_bf16 v[26:29], v[142:145], v[214:217], v[26:29]
	v_mfma_f32_16x16x32_bf16 v[22:25], v[166:169], v[210:213], v[22:25]
	v_mfma_f32_16x16x32_bf16 v[22:25], v[170:173], v[214:217], v[22:25]
	v_mfma_f32_16x16x32_bf16 v[18:21], v[186:189], v[210:213], v[18:21]
	v_mfma_f32_16x16x32_bf16 v[18:21], v[190:193], v[214:217], v[18:21]
	v_mfma_f32_16x16x32_bf16 v[14:17], v[130:133], v[218:221], v[14:17]
	v_mfma_f32_16x16x32_bf16 v[14:17], v[134:137], v[222:225], v[14:17]
	v_mfma_f32_16x16x32_bf16 v[10:13], v[138:141], v[218:221], v[10:13]
	v_mfma_f32_16x16x32_bf16 v[10:13], v[142:145], v[222:225], v[10:13]
	v_mfma_f32_16x16x32_bf16 v[6:9], v[166:169], v[218:221], v[6:9]
	v_mfma_f32_16x16x32_bf16 v[6:9], v[170:173], v[222:225], v[6:9]
	v_mfma_f32_16x16x32_bf16 v[2:5], v[186:189], v[218:221], v[2:5]
	v_mfma_f32_16x16x32_bf16 v[2:5], v[190:193], v[222:225], v[2:5]
	s_barrier
	s_add_i32 s76, 0, 0x18000
	s_add_i32 s77, 0, 0x1c000
	ds_read_b128 v[130:133], v246
	ds_read_b128 v[134:137], v246 offset:1024
	ds_read_b128 v[138:141], v246 offset:2048
	ds_read_b128 v[142:145], v246 offset:3072
	ds_read_b128 v[166:169], v247
	ds_read_b128 v[170:173], v247 offset:1024
	ds_read_b128 v[186:189], v247 offset:2048
	ds_read_b128 v[190:193], v247 offset:3072
	s_add_u32 s74, s84, 0x100000
	s_addc_u32 s75, s85, 0
	s_mov_b32 m0, s33
	ds_read_b128 v[194:197], v177 offset:32768
	ds_read_b128 v[198:201], v177 offset:33792
	ds_read_b128 v[202:205], v177 offset:34816
	ds_read_b128 v[206:209], v177 offset:35840
	ds_read_b128 v[210:213], v177 offset:36864
	ds_read_b128 v[214:217], v177 offset:37888
	ds_read_b128 v[218:221], v177 offset:38912
	ds_read_b128 v[222:225], v177 offset:39936
	global_load_lds_dwordx4 v146, s[74:75]
	s_mov_b32 m0, s35
	s_nop 0
	global_load_lds_dwordx4 v150, s[74:75]
	s_waitcnt vmcnt(8) lgkmcnt(0)
	s_barrier
	v_mfma_f32_16x16x32_bf16 v[126:129], v[130:133], v[194:197], v[126:129]
	v_mfma_f32_16x16x32_bf16 v[126:129], v[134:137], v[198:201], v[126:129]
	v_mfma_f32_16x16x32_bf16 v[122:125], v[138:141], v[194:197], v[122:125]
	v_mfma_f32_16x16x32_bf16 v[122:125], v[142:145], v[198:201], v[122:125]
	v_mfma_f32_16x16x32_bf16 v[118:121], v[166:169], v[194:197], v[118:121]
	v_mfma_f32_16x16x32_bf16 v[118:121], v[170:173], v[198:201], v[118:121]
	v_mfma_f32_16x16x32_bf16 v[114:117], v[186:189], v[194:197], v[114:117]
	v_mfma_f32_16x16x32_bf16 v[114:117], v[190:193], v[198:201], v[114:117]
	v_mfma_f32_16x16x32_bf16 v[110:113], v[130:133], v[202:205], v[110:113]
	v_mfma_f32_16x16x32_bf16 v[110:113], v[134:137], v[206:209], v[110:113]
	v_mfma_f32_16x16x32_bf16 v[106:109], v[138:141], v[202:205], v[106:109]
	v_mfma_f32_16x16x32_bf16 v[106:109], v[142:145], v[206:209], v[106:109]
	v_mfma_f32_16x16x32_bf16 v[102:105], v[166:169], v[202:205], v[102:105]
	v_mfma_f32_16x16x32_bf16 v[102:105], v[170:173], v[206:209], v[102:105]
	v_mfma_f32_16x16x32_bf16 v[98:101], v[186:189], v[202:205], v[98:101]
	v_mfma_f32_16x16x32_bf16 v[98:101], v[190:193], v[206:209], v[98:101]
	v_mfma_f32_16x16x32_bf16 v[94:97], v[130:133], v[210:213], v[94:97]
	v_mfma_f32_16x16x32_bf16 v[94:97], v[134:137], v[214:217], v[94:97]
	v_mfma_f32_16x16x32_bf16 v[90:93], v[138:141], v[210:213], v[90:93]
	v_mfma_f32_16x16x32_bf16 v[90:93], v[142:145], v[214:217], v[90:93]
	v_mfma_f32_16x16x32_bf16 v[86:89], v[166:169], v[210:213], v[86:89]
	v_mfma_f32_16x16x32_bf16 v[86:89], v[170:173], v[214:217], v[86:89]
	v_mfma_f32_16x16x32_bf16 v[82:85], v[186:189], v[210:213], v[82:85]
	v_mfma_f32_16x16x32_bf16 v[82:85], v[190:193], v[214:217], v[82:85]
	v_mfma_f32_16x16x32_bf16 v[78:81], v[130:133], v[218:221], v[78:81]
	v_mfma_f32_16x16x32_bf16 v[78:81], v[134:137], v[222:225], v[78:81]
	v_mfma_f32_16x16x32_bf16 v[74:77], v[138:141], v[218:221], v[74:77]
	v_mfma_f32_16x16x32_bf16 v[74:77], v[142:145], v[222:225], v[74:77]
	v_mfma_f32_16x16x32_bf16 v[70:73], v[166:169], v[218:221], v[70:73]
	v_mfma_f32_16x16x32_bf16 v[70:73], v[170:173], v[222:225], v[70:73]
	v_mfma_f32_16x16x32_bf16 v[66:69], v[186:189], v[218:221], v[66:69]
	v_mfma_f32_16x16x32_bf16 v[66:69], v[190:193], v[222:225], v[66:69]
	s_barrier
	s_add_i32 s74, s76, s3
	s_mov_b32 m0, s74
	ds_read_b128 v[194:197], v177 offset:49152
	ds_read_b128 v[198:201], v177 offset:50176
	ds_read_b128 v[202:205], v177 offset:51200
	ds_read_b128 v[206:209], v177 offset:52224
	ds_read_b128 v[210:213], v177 offset:53248
	ds_read_b128 v[214:217], v177 offset:54272
	ds_read_b128 v[218:221], v177 offset:55296
	ds_read_b128 v[222:225], v177 offset:56320
	global_load_lds_dwordx4 v148, s[98:99]
	s_add_i32 m0, s74, 0x2000
	s_add_u32 s74, s82, 0x100080
	s_addc_u32 s75, s83, 0
	s_add_i32 s76, s77, s3
	global_load_lds_dwordx4 v152, s[98:99]
	s_mov_b32 m0, s76
	s_nop 0
	global_load_lds_dwordx4 v148, s[74:75]
	s_add_i32 m0, s76, 0x2000
	s_nop 0
	global_load_lds_dwordx4 v152, s[74:75]
	s_mov_b32 m0, s62
	s_nop 0
	global_load_lds_dwordx4 v146, s[100:101]
	s_mov_b32 m0, s63
	s_nop 0
	global_load_lds_dwordx4 v150, s[100:101]
	s_waitcnt vmcnt(8) lgkmcnt(0)
	s_barrier
	v_mfma_f32_16x16x32_bf16 v[62:65], v[130:133], v[194:197], v[62:65]
	v_mfma_f32_16x16x32_bf16 v[62:65], v[134:137], v[198:201], v[62:65]
	v_mfma_f32_16x16x32_bf16 v[58:61], v[138:141], v[194:197], v[58:61]
	v_mfma_f32_16x16x32_bf16 v[58:61], v[142:145], v[198:201], v[58:61]
	v_mfma_f32_16x16x32_bf16 v[54:57], v[166:169], v[194:197], v[54:57]
	v_mfma_f32_16x16x32_bf16 v[54:57], v[170:173], v[198:201], v[54:57]
	v_mfma_f32_16x16x32_bf16 v[50:53], v[186:189], v[194:197], v[50:53]
	v_mfma_f32_16x16x32_bf16 v[50:53], v[190:193], v[198:201], v[50:53]
	v_mfma_f32_16x16x32_bf16 v[46:49], v[130:133], v[202:205], v[46:49]
	v_mfma_f32_16x16x32_bf16 v[46:49], v[134:137], v[206:209], v[46:49]
	v_mfma_f32_16x16x32_bf16 v[42:45], v[138:141], v[202:205], v[42:45]
	v_mfma_f32_16x16x32_bf16 v[42:45], v[142:145], v[206:209], v[42:45]
	v_mfma_f32_16x16x32_bf16 v[38:41], v[166:169], v[202:205], v[38:41]
	v_mfma_f32_16x16x32_bf16 v[38:41], v[170:173], v[206:209], v[38:41]
	v_mfma_f32_16x16x32_bf16 v[34:37], v[186:189], v[202:205], v[34:37]
	v_mfma_f32_16x16x32_bf16 v[34:37], v[190:193], v[206:209], v[34:37]
	v_mfma_f32_16x16x32_bf16 v[30:33], v[130:133], v[210:213], v[30:33]
	v_mfma_f32_16x16x32_bf16 v[30:33], v[134:137], v[214:217], v[30:33]
	v_mfma_f32_16x16x32_bf16 v[26:29], v[138:141], v[210:213], v[26:29]
	v_mfma_f32_16x16x32_bf16 v[26:29], v[142:145], v[214:217], v[26:29]
	v_mfma_f32_16x16x32_bf16 v[22:25], v[166:169], v[210:213], v[22:25]
	v_mfma_f32_16x16x32_bf16 v[22:25], v[170:173], v[214:217], v[22:25]
	v_mfma_f32_16x16x32_bf16 v[18:21], v[186:189], v[210:213], v[18:21]
	v_mfma_f32_16x16x32_bf16 v[18:21], v[190:193], v[214:217], v[18:21]
	v_mfma_f32_16x16x32_bf16 v[14:17], v[130:133], v[218:221], v[14:17]
	v_mfma_f32_16x16x32_bf16 v[14:17], v[134:137], v[222:225], v[14:17]
	v_mfma_f32_16x16x32_bf16 v[10:13], v[138:141], v[218:221], v[10:13]
	v_mfma_f32_16x16x32_bf16 v[10:13], v[142:145], v[222:225], v[10:13]
	v_mfma_f32_16x16x32_bf16 v[6:9], v[166:169], v[218:221], v[6:9]
	v_mfma_f32_16x16x32_bf16 v[6:9], v[170:173], v[222:225], v[6:9]
	v_mfma_f32_16x16x32_bf16 v[2:5], v[186:189], v[218:221], v[2:5]
	v_mfma_f32_16x16x32_bf16 v[2:5], v[190:193], v[222:225], v[2:5]
	s_barrier
	s_add_i32 s73, s73, 2
	s_add_u32 s50, s50, 0x100
	s_addc_u32 s51, s51, 0
	s_add_u32 s71, s71, 0x100
	s_addc_u32 s72, s72, 0
	s_cmp_gt_u32 s73, 61
	s_cbranch_scc0 .LBB0_2109
	s_setprio 0
	s_and_b64 vcc, exec, s[40:41]
	s_cbranch_vccz .LBB0_2112
	s_barrier

.LBB0_2212:
	ds_read_b128 v[150:153], v162
	ds_read_b128 v[168:171], v162 offset:1024
	ds_read_b128 v[172:175], v162 offset:2048
	ds_read_b128 v[176:179], v162 offset:3072
	ds_read_b128 v[186:189], v163
	ds_read_b128 v[190:193], v163 offset:1024
	ds_read_b128 v[194:197], v163 offset:2048
	ds_read_b128 v[198:201], v163 offset:3072
	s_add_u32 s50, s6, 0xfff00080
	s_addc_u32 s51, s7, -1
	s_cmp_eq_u32 s79, 60
	s_cselect_b32 s81, s45, s51
	s_cselect_b32 s80, s75, s50
	s_cselect_b32 s51, s43, s78
	s_cselect_b32 s50, s76, s77
	s_add_i32 m0, s33, 0xc000
	ds_read_b128 v[202:205], v164
	ds_read_b128 v[206:209], v164 offset:1024
	ds_read_b128 v[210:213], v164 offset:2048
	ds_read_b128 v[214:217], v164 offset:3072
	ds_read_b128 v[218:221], v164 offset:4096
	ds_read_b128 v[222:225], v164 offset:5120
	ds_read_b128 v[226:229], v164 offset:6144
	ds_read_b128 v[230:233], v164 offset:7168
	global_load_lds_dwordx4 v142, s[6:7]
	s_add_i32 m0, s33, 0xe000
	s_nop 0
	global_load_lds_dwordx4 v144, s[6:7]
	s_waitcnt vmcnt(8) lgkmcnt(0)
	s_barrier
	v_mfma_f32_16x16x32_bf16 v[126:129], v[150:153], v[202:205], v[126:129]
	v_mfma_f32_16x16x32_bf16 v[126:129], v[168:171], v[206:209], v[126:129]
	v_mfma_f32_16x16x32_bf16 v[118:121], v[172:175], v[202:205], v[118:121]
	v_mfma_f32_16x16x32_bf16 v[118:121], v[176:179], v[206:209], v[118:121]
	v_mfma_f32_16x16x32_bf16 v[122:125], v[186:189], v[202:205], v[122:125]
	v_mfma_f32_16x16x32_bf16 v[122:125], v[190:193], v[206:209], v[122:125]
	v_mfma_f32_16x16x32_bf16 v[114:117], v[194:197], v[202:205], v[114:117]
	v_mfma_f32_16x16x32_bf16 v[114:117], v[198:201], v[206:209], v[114:117]
	v_mfma_f32_16x16x32_bf16 v[110:113], v[150:153], v[210:213], v[110:113]
	v_mfma_f32_16x16x32_bf16 v[110:113], v[168:171], v[214:217], v[110:113]
	v_mfma_f32_16x16x32_bf16 v[102:105], v[172:175], v[210:213], v[102:105]
	v_mfma_f32_16x16x32_bf16 v[102:105], v[176:179], v[214:217], v[102:105]
	v_mfma_f32_16x16x32_bf16 v[106:109], v[186:189], v[210:213], v[106:109]
	v_mfma_f32_16x16x32_bf16 v[106:109], v[190:193], v[214:217], v[106:109]
	v_mfma_f32_16x16x32_bf16 v[98:101], v[194:197], v[210:213], v[98:101]
	v_mfma_f32_16x16x32_bf16 v[98:101], v[198:201], v[214:217], v[98:101]
	v_mfma_f32_16x16x32_bf16 v[94:97], v[150:153], v[218:221], v[94:97]
	v_mfma_f32_16x16x32_bf16 v[94:97], v[168:171], v[222:225], v[94:97]
	v_mfma_f32_16x16x32_bf16 v[86:89], v[172:175], v[218:221], v[86:89]
	v_mfma_f32_16x16x32_bf16 v[86:89], v[176:179], v[222:225], v[86:89]
	v_mfma_f32_16x16x32_bf16 v[90:93], v[186:189], v[218:221], v[90:93]
	v_mfma_f32_16x16x32_bf16 v[90:93], v[190:193], v[222:225], v[90:93]
	v_mfma_f32_16x16x32_bf16 v[82:85], v[194:197], v[218:221], v[82:85]
	v_mfma_f32_16x16x32_bf16 v[82:85], v[198:201], v[222:225], v[82:85]
	v_mfma_f32_16x16x32_bf16 v[78:81], v[150:153], v[226:229], v[78:81]
	v_mfma_f32_16x16x32_bf16 v[78:81], v[168:171], v[230:233], v[78:81]
	v_mfma_f32_16x16x32_bf16 v[70:73], v[172:175], v[226:229], v[70:73]
	v_mfma_f32_16x16x32_bf16 v[70:73], v[176:179], v[230:233], v[70:73]
	v_mfma_f32_16x16x32_bf16 v[74:77], v[186:189], v[226:229], v[74:77]
	v_mfma_f32_16x16x32_bf16 v[74:77], v[190:193], v[230:233], v[74:77]
	v_mfma_f32_16x16x32_bf16 v[66:69], v[194:197], v[226:229], v[66:69]
	v_mfma_f32_16x16x32_bf16 v[66:69], v[198:201], v[230:233], v[66:69]
	s_barrier
	s_add_i32 s82, s68, s29
	s_add_u32 s98, s50, 0x80
	s_addc_u32 s99, s51, 0
	s_mov_b32 m0, s82
	ds_read_b128 v[202:205], v164 offset:16384
	ds_read_b128 v[206:209], v164 offset:17408
	ds_read_b128 v[210:213], v164 offset:18432
	ds_read_b128 v[214:217], v164 offset:19456
	ds_read_b128 v[218:221], v164 offset:20480
	ds_read_b128 v[222:225], v164 offset:21504
	ds_read_b128 v[226:229], v164 offset:22528
	ds_read_b128 v[230:233], v164 offset:23552
	global_load_lds_dwordx4 v134, s[50:51]
	s_add_i32 m0, s82, 0x2000
	s_add_u32 s82, s50, 0x100000
	s_addc_u32 s83, s51, 0
	s_add_i32 s84, s69, s29
	global_load_lds_dwordx4 v138, s[50:51]
	s_mov_b32 m0, s84
	global_load_lds_dwordx4 v134, s[82:83]
	s_add_i32 m0, s84, 0x2000
	s_nop 0
	global_load_lds_dwordx4 v138, s[82:83]
	s_add_u32 s100, s80, 0x80
	s_addc_u32 s101, s81, 0
	s_mov_b32 m0, s33
	s_nop 0
	global_load_lds_dwordx4 v132, s[80:81]
	s_mov_b32 m0, s35
	s_nop 0
	global_load_lds_dwordx4 v136, s[80:81]
	s_waitcnt vmcnt(8) lgkmcnt(0)
	s_barrier
	v_mfma_f32_16x16x32_bf16 v[62:65], v[150:153], v[202:205], v[62:65]
	v_mfma_f32_16x16x32_bf16 v[62:65], v[168:171], v[206:209], v[62:65]
	v_mfma_f32_16x16x32_bf16 v[54:57], v[172:175], v[202:205], v[54:57]
	v_mfma_f32_16x16x32_bf16 v[54:57], v[176:179], v[206:209], v[54:57]
	v_mfma_f32_16x16x32_bf16 v[58:61], v[186:189], v[202:205], v[58:61]
	v_mfma_f32_16x16x32_bf16 v[58:61], v[190:193], v[206:209], v[58:61]
	v_mfma_f32_16x16x32_bf16 v[50:53], v[194:197], v[202:205], v[50:53]
	v_mfma_f32_16x16x32_bf16 v[50:53], v[198:201], v[206:209], v[50:53]
	v_mfma_f32_16x16x32_bf16 v[46:49], v[150:153], v[210:213], v[46:49]
	v_mfma_f32_16x16x32_bf16 v[46:49], v[168:171], v[214:217], v[46:49]
	v_mfma_f32_16x16x32_bf16 v[38:41], v[172:175], v[210:213], v[38:41]
	v_mfma_f32_16x16x32_bf16 v[38:41], v[176:179], v[214:217], v[38:41]
	v_mfma_f32_16x16x32_bf16 v[42:45], v[186:189], v[210:213], v[42:45]
	v_mfma_f32_16x16x32_bf16 v[42:45], v[190:193], v[214:217], v[42:45]
	v_mfma_f32_16x16x32_bf16 v[34:37], v[194:197], v[210:213], v[34:37]
	v_mfma_f32_16x16x32_bf16 v[34:37], v[198:201], v[214:217], v[34:37]
	v_mfma_f32_16x16x32_bf16 v[30:33], v[150:153], v[218:221], v[30:33]
	v_mfma_f32_16x16x32_bf16 v[30:33], v[168:171], v[222:225], v[30:33]
	v_mfma_f32_16x16x32_bf16 v[22:25], v[172:175], v[218:221], v[22:25]
	v_mfma_f32_16x16x32_bf16 v[22:25], v[176:179], v[222:225], v[22:25]
	v_mfma_f32_16x16x32_bf16 v[26:29], v[186:189], v[218:221], v[26:29]
	v_mfma_f32_16x16x32_bf16 v[26:29], v[190:193], v[222:225], v[26:29]
	v_mfma_f32_16x16x32_bf16 v[18:21], v[194:197], v[218:221], v[18:21]
	v_mfma_f32_16x16x32_bf16 v[18:21], v[198:201], v[222:225], v[18:21]
	v_mfma_f32_16x16x32_bf16 v[14:17], v[150:153], v[226:229], v[14:17]
	v_mfma_f32_16x16x32_bf16 v[14:17], v[168:171], v[230:233], v[14:17]
	v_mfma_f32_16x16x32_bf16 v[6:9], v[172:175], v[226:229], v[6:9]
	v_mfma_f32_16x16x32_bf16 v[6:9], v[176:179], v[230:233], v[6:9]
	v_mfma_f32_16x16x32_bf16 v[10:13], v[186:189], v[226:229], v[10:13]
	v_mfma_f32_16x16x32_bf16 v[10:13], v[190:193], v[230:233], v[10:13]
	v_mfma_f32_16x16x32_bf16 v[2:5], v[194:197], v[226:229], v[2:5]
	v_mfma_f32_16x16x32_bf16 v[2:5], v[198:201], v[230:233], v[2:5]
	s_barrier
	s_add_i32 s82, 0, 0x18000
	s_add_i32 s83, 0, 0x1c000
	ds_read_b128 v[150:153], v246
	ds_read_b128 v[168:171], v246 offset:1024
	ds_read_b128 v[172:175], v246 offset:2048
	ds_read_b128 v[176:179], v246 offset:3072
	ds_read_b128 v[186:189], v247
	ds_read_b128 v[190:193], v247 offset:1024
	ds_read_b128 v[194:197], v247 offset:2048
	ds_read_b128 v[198:201], v247 offset:3072
	s_add_u32 s80, s80, 0x100000
	s_addc_u32 s81, s81, 0
	s_mov_b32 m0, s59
	ds_read_b128 v[202:205], v164 offset:32768
	ds_read_b128 v[206:209], v164 offset:33792
	ds_read_b128 v[210:213], v164 offset:34816
	ds_read_b128 v[214:217], v164 offset:35840
	ds_read_b128 v[218:221], v164 offset:36864
	ds_read_b128 v[222:225], v164 offset:37888
	ds_read_b128 v[226:229], v164 offset:38912
	ds_read_b128 v[230:233], v164 offset:39936
	global_load_lds_dwordx4 v132, s[80:81]
	s_mov_b32 m0, s62
	s_nop 0
	global_load_lds_dwordx4 v136, s[80:81]
	s_waitcnt vmcnt(8) lgkmcnt(0)
	s_barrier
	v_mfma_f32_16x16x32_bf16 v[126:129], v[150:153], v[202:205], v[126:129]
	v_mfma_f32_16x16x32_bf16 v[126:129], v[168:171], v[206:209], v[126:129]
	v_mfma_f32_16x16x32_bf16 v[118:121], v[172:175], v[202:205], v[118:121]
	v_mfma_f32_16x16x32_bf16 v[118:121], v[176:179], v[206:209], v[118:121]
	v_mfma_f32_16x16x32_bf16 v[122:125], v[186:189], v[202:205], v[122:125]
	v_mfma_f32_16x16x32_bf16 v[122:125], v[190:193], v[206:209], v[122:125]
	v_mfma_f32_16x16x32_bf16 v[114:117], v[194:197], v[202:205], v[114:117]
	v_mfma_f32_16x16x32_bf16 v[114:117], v[198:201], v[206:209], v[114:117]
	v_mfma_f32_16x16x32_bf16 v[110:113], v[150:153], v[210:213], v[110:113]
	v_mfma_f32_16x16x32_bf16 v[110:113], v[168:171], v[214:217], v[110:113]
	v_mfma_f32_16x16x32_bf16 v[102:105], v[172:175], v[210:213], v[102:105]
	v_mfma_f32_16x16x32_bf16 v[102:105], v[176:179], v[214:217], v[102:105]
	v_mfma_f32_16x16x32_bf16 v[106:109], v[186:189], v[210:213], v[106:109]
	v_mfma_f32_16x16x32_bf16 v[106:109], v[190:193], v[214:217], v[106:109]
	v_mfma_f32_16x16x32_bf16 v[98:101], v[194:197], v[210:213], v[98:101]
	v_mfma_f32_16x16x32_bf16 v[98:101], v[198:201], v[214:217], v[98:101]
	v_mfma_f32_16x16x32_bf16 v[94:97], v[150:153], v[218:221], v[94:97]
	v_mfma_f32_16x16x32_bf16 v[94:97], v[168:171], v[222:225], v[94:97]
	v_mfma_f32_16x16x32_bf16 v[86:89], v[172:175], v[218:221], v[86:89]
	v_mfma_f32_16x16x32_bf16 v[86:89], v[176:179], v[222:225], v[86:89]
	v_mfma_f32_16x16x32_bf16 v[90:93], v[186:189], v[218:221], v[90:93]
	v_mfma_f32_16x16x32_bf16 v[90:93], v[190:193], v[222:225], v[90:93]
	v_mfma_f32_16x16x32_bf16 v[82:85], v[194:197], v[218:221], v[82:85]
	v_mfma_f32_16x16x32_bf16 v[82:85], v[198:201], v[222:225], v[82:85]
	v_mfma_f32_16x16x32_bf16 v[78:81], v[150:153], v[226:229], v[78:81]
	v_mfma_f32_16x16x32_bf16 v[78:81], v[168:171], v[230:233], v[78:81]
	v_mfma_f32_16x16x32_bf16 v[70:73], v[172:175], v[226:229], v[70:73]
	v_mfma_f32_16x16x32_bf16 v[70:73], v[176:179], v[230:233], v[70:73]
	v_mfma_f32_16x16x32_bf16 v[74:77], v[186:189], v[226:229], v[74:77]
	v_mfma_f32_16x16x32_bf16 v[74:77], v[190:193], v[230:233], v[74:77]
	v_mfma_f32_16x16x32_bf16 v[66:69], v[194:197], v[226:229], v[66:69]
	v_mfma_f32_16x16x32_bf16 v[66:69], v[198:201], v[230:233], v[66:69]
	s_barrier
	s_add_i32 s80, s82, s29
	s_mov_b32 m0, s80
	ds_read_b128 v[202:205], v164 offset:49152
	ds_read_b128 v[206:209], v164 offset:50176
	ds_read_b128 v[210:213], v164 offset:51200
	ds_read_b128 v[214:217], v164 offset:52224
	ds_read_b128 v[218:221], v164 offset:53248
	ds_read_b128 v[222:225], v164 offset:54272
	ds_read_b128 v[226:229], v164 offset:55296
	ds_read_b128 v[230:233], v164 offset:56320
	global_load_lds_dwordx4 v134, s[98:99]
	s_add_i32 m0, s80, 0x2000
	s_add_u32 s50, s50, 0x100080
	s_addc_u32 s51, s51, 0
	s_add_i32 s80, s83, s29
	global_load_lds_dwordx4 v138, s[98:99]
	s_mov_b32 m0, s80
	s_nop 0
	global_load_lds_dwordx4 v134, s[50:51]
	s_add_i32 m0, s80, 0x2000
	s_nop 0
	global_load_lds_dwordx4 v138, s[50:51]
	s_mov_b32 m0, s65
	s_nop 0
	global_load_lds_dwordx4 v132, s[100:101]
	s_mov_b32 m0, s66
	s_nop 0
	global_load_lds_dwordx4 v136, s[100:101]
	s_waitcnt vmcnt(8) lgkmcnt(0)
	s_barrier
	v_mfma_f32_16x16x32_bf16 v[62:65], v[150:153], v[202:205], v[62:65]
	v_mfma_f32_16x16x32_bf16 v[62:65], v[168:171], v[206:209], v[62:65]
	v_mfma_f32_16x16x32_bf16 v[54:57], v[172:175], v[202:205], v[54:57]
	v_mfma_f32_16x16x32_bf16 v[54:57], v[176:179], v[206:209], v[54:57]
	v_mfma_f32_16x16x32_bf16 v[58:61], v[186:189], v[202:205], v[58:61]
	v_mfma_f32_16x16x32_bf16 v[58:61], v[190:193], v[206:209], v[58:61]
	v_mfma_f32_16x16x32_bf16 v[50:53], v[194:197], v[202:205], v[50:53]
	v_mfma_f32_16x16x32_bf16 v[50:53], v[198:201], v[206:209], v[50:53]
	v_mfma_f32_16x16x32_bf16 v[46:49], v[150:153], v[210:213], v[46:49]
	v_mfma_f32_16x16x32_bf16 v[46:49], v[168:171], v[214:217], v[46:49]
	v_mfma_f32_16x16x32_bf16 v[38:41], v[172:175], v[210:213], v[38:41]
	v_mfma_f32_16x16x32_bf16 v[38:41], v[176:179], v[214:217], v[38:41]
	v_mfma_f32_16x16x32_bf16 v[42:45], v[186:189], v[210:213], v[42:45]
	v_mfma_f32_16x16x32_bf16 v[42:45], v[190:193], v[214:217], v[42:45]
	v_mfma_f32_16x16x32_bf16 v[34:37], v[194:197], v[210:213], v[34:37]
	v_mfma_f32_16x16x32_bf16 v[34:37], v[198:201], v[214:217], v[34:37]
	v_mfma_f32_16x16x32_bf16 v[30:33], v[150:153], v[218:221], v[30:33]
	v_mfma_f32_16x16x32_bf16 v[30:33], v[168:171], v[222:225], v[30:33]
	v_mfma_f32_16x16x32_bf16 v[22:25], v[172:175], v[218:221], v[22:25]
	v_mfma_f32_16x16x32_bf16 v[22:25], v[176:179], v[222:225], v[22:25]
	v_mfma_f32_16x16x32_bf16 v[26:29], v[186:189], v[218:221], v[26:29]
	v_mfma_f32_16x16x32_bf16 v[26:29], v[190:193], v[222:225], v[26:29]
	v_mfma_f32_16x16x32_bf16 v[18:21], v[194:197], v[218:221], v[18:21]
	v_mfma_f32_16x16x32_bf16 v[18:21], v[198:201], v[222:225], v[18:21]
	v_mfma_f32_16x16x32_bf16 v[14:17], v[150:153], v[226:229], v[14:17]
	v_mfma_f32_16x16x32_bf16 v[14:17], v[168:171], v[230:233], v[14:17]
	v_mfma_f32_16x16x32_bf16 v[6:9], v[172:175], v[226:229], v[6:9]
	v_mfma_f32_16x16x32_bf16 v[6:9], v[176:179], v[230:233], v[6:9]
	v_mfma_f32_16x16x32_bf16 v[10:13], v[186:189], v[226:229], v[10:13]
	v_mfma_f32_16x16x32_bf16 v[10:13], v[190:193], v[230:233], v[10:13]
	v_mfma_f32_16x16x32_bf16 v[2:5], v[194:197], v[226:229], v[2:5]
	v_mfma_f32_16x16x32_bf16 v[2:5], v[198:201], v[230:233], v[2:5]
	s_barrier
	s_add_i32 s79, s79, 2
	s_add_u32 s6, s6, 0x100
	s_addc_u32 s7, s7, 0
	s_add_u32 s77, s77, 0x100
	s_addc_u32 s78, s78, 0
	s_cmp_gt_u32 s79, 61
	s_cbranch_scc0 .LBB0_2212
	s_setprio 0
	s_and_b64 vcc, exec, s[40:41]
	s_cbranch_vccz .LBB0_2215
	s_barrier

.LBB0_2340:
	ds_read_b128 v[130:133], v163
	ds_read_b128 v[134:137], v163 offset:1024
	ds_read_b128 v[138:141], v163 offset:2048
	ds_read_b128 v[142:145], v163 offset:3072
	ds_read_b128 v[146:149], v190
	ds_read_b128 v[150:153], v190 offset:1024
	ds_read_b128 v[174:177], v190 offset:2048
	ds_read_b128 v[178:181], v190 offset:3072
	s_add_u32 s42, s40, 0xffd50080
	s_addc_u32 s43, s41, -1
	s_cmpk_eq_i32 s71, 0xa8
	s_cselect_b32 s45, s1, s43
	s_cselect_b32 s44, s0, s42
	s_cselect_b32 s43, s39, s70
	s_cselect_b32 s42, s38, s12
	s_add_i32 m0, s46, 0xc000
	ds_read_b128 v[186:189], v191
	ds_read_b128 v[194:197], v191 offset:1024
	ds_read_b128 v[198:201], v191 offset:2048
	ds_read_b128 v[202:205], v191 offset:3072
	ds_read_b128 v[206:209], v191 offset:4096
	ds_read_b128 v[210:213], v191 offset:5120
	ds_read_b128 v[214:217], v191 offset:6144
	ds_read_b128 v[218:221], v191 offset:7168
	global_load_lds_dwordx4 v166, s[40:41]
	s_add_i32 m0, s46, 0xe000
	s_nop 0
	global_load_lds_dwordx4 v168, s[40:41]
	s_waitcnt vmcnt(8) lgkmcnt(0)
	s_barrier
	v_mfma_f32_16x16x32_bf16 v[126:129], v[130:133], v[186:189], v[126:129]
	v_mfma_f32_16x16x32_bf16 v[126:129], v[134:137], v[194:197], v[126:129]
	v_mfma_f32_16x16x32_bf16 v[122:125], v[138:141], v[186:189], v[122:125]
	v_mfma_f32_16x16x32_bf16 v[122:125], v[142:145], v[194:197], v[122:125]
	v_mfma_f32_16x16x32_bf16 v[118:121], v[146:149], v[186:189], v[118:121]
	v_mfma_f32_16x16x32_bf16 v[118:121], v[150:153], v[194:197], v[118:121]
	v_mfma_f32_16x16x32_bf16 v[114:117], v[174:177], v[186:189], v[114:117]
	v_mfma_f32_16x16x32_bf16 v[114:117], v[178:181], v[194:197], v[114:117]
	v_mfma_f32_16x16x32_bf16 v[110:113], v[130:133], v[198:201], v[110:113]
	v_mfma_f32_16x16x32_bf16 v[110:113], v[134:137], v[202:205], v[110:113]
	v_mfma_f32_16x16x32_bf16 v[106:109], v[138:141], v[198:201], v[106:109]
	v_mfma_f32_16x16x32_bf16 v[106:109], v[142:145], v[202:205], v[106:109]
	v_mfma_f32_16x16x32_bf16 v[102:105], v[146:149], v[198:201], v[102:105]
	v_mfma_f32_16x16x32_bf16 v[102:105], v[150:153], v[202:205], v[102:105]
	v_mfma_f32_16x16x32_bf16 v[98:101], v[174:177], v[198:201], v[98:101]
	v_mfma_f32_16x16x32_bf16 v[98:101], v[178:181], v[202:205], v[98:101]
	v_mfma_f32_16x16x32_bf16 v[94:97], v[130:133], v[206:209], v[94:97]
	v_mfma_f32_16x16x32_bf16 v[94:97], v[134:137], v[210:213], v[94:97]
	v_mfma_f32_16x16x32_bf16 v[90:93], v[138:141], v[206:209], v[90:93]
	v_mfma_f32_16x16x32_bf16 v[90:93], v[142:145], v[210:213], v[90:93]
	v_mfma_f32_16x16x32_bf16 v[86:89], v[146:149], v[206:209], v[86:89]
	v_mfma_f32_16x16x32_bf16 v[86:89], v[150:153], v[210:213], v[86:89]
	v_mfma_f32_16x16x32_bf16 v[82:85], v[174:177], v[206:209], v[82:85]
	v_mfma_f32_16x16x32_bf16 v[82:85], v[178:181], v[210:213], v[82:85]
	v_mfma_f32_16x16x32_bf16 v[78:81], v[130:133], v[214:217], v[78:81]
	v_mfma_f32_16x16x32_bf16 v[78:81], v[134:137], v[218:221], v[78:81]
	v_mfma_f32_16x16x32_bf16 v[74:77], v[138:141], v[214:217], v[74:77]
	v_mfma_f32_16x16x32_bf16 v[74:77], v[142:145], v[218:221], v[74:77]
	v_mfma_f32_16x16x32_bf16 v[70:73], v[146:149], v[214:217], v[70:73]
	v_mfma_f32_16x16x32_bf16 v[70:73], v[150:153], v[218:221], v[70:73]
	v_mfma_f32_16x16x32_bf16 v[66:69], v[174:177], v[214:217], v[66:69]
	v_mfma_f32_16x16x32_bf16 v[66:69], v[178:181], v[218:221], v[66:69]
	s_barrier
	s_add_i32 s72, s65, s35
	s_add_u32 s98, s42, 0x80
	s_addc_u32 s99, s43, 0
	s_mov_b32 m0, s72
	ds_read_b128 v[186:189], v191 offset:16384
	ds_read_b128 v[194:197], v191 offset:17408
	ds_read_b128 v[198:201], v191 offset:18432
	ds_read_b128 v[202:205], v191 offset:19456
	ds_read_b128 v[206:209], v191 offset:20480
	ds_read_b128 v[210:213], v191 offset:21504
	ds_read_b128 v[214:217], v191 offset:22528
	ds_read_b128 v[218:221], v191 offset:23552
	global_load_lds_dwordx4 v156, s[42:43]
	s_add_i32 m0, s72, 0x2000
	s_add_u32 s72, s42, 0x2b0000
	s_addc_u32 s73, s43, 0
	s_add_i32 s74, s66, s35
	global_load_lds_dwordx4 v160, s[42:43]
	s_mov_b32 m0, s74
	global_load_lds_dwordx4 v156, s[72:73]
	s_add_i32 m0, s74, 0x2000
	s_nop 0
	global_load_lds_dwordx4 v160, s[72:73]
	s_add_u32 s100, s44, 0x80
	s_addc_u32 s101, s45, 0
	s_mov_b32 m0, s46
	s_nop 0
	global_load_lds_dwordx4 v154, s[44:45]
	s_mov_b32 m0, s47
	s_nop 0
	global_load_lds_dwordx4 v158, s[44:45]
	s_waitcnt vmcnt(8) lgkmcnt(0)
	s_barrier
	v_mfma_f32_16x16x32_bf16 v[62:65], v[130:133], v[186:189], v[62:65]
	v_mfma_f32_16x16x32_bf16 v[62:65], v[134:137], v[194:197], v[62:65]
	v_mfma_f32_16x16x32_bf16 v[58:61], v[138:141], v[186:189], v[58:61]
	v_mfma_f32_16x16x32_bf16 v[58:61], v[142:145], v[194:197], v[58:61]
	v_mfma_f32_16x16x32_bf16 v[54:57], v[146:149], v[186:189], v[54:57]
	v_mfma_f32_16x16x32_bf16 v[54:57], v[150:153], v[194:197], v[54:57]
	v_mfma_f32_16x16x32_bf16 v[50:53], v[174:177], v[186:189], v[50:53]
	v_mfma_f32_16x16x32_bf16 v[50:53], v[178:181], v[194:197], v[50:53]
	v_mfma_f32_16x16x32_bf16 v[46:49], v[130:133], v[198:201], v[46:49]
	v_mfma_f32_16x16x32_bf16 v[46:49], v[134:137], v[202:205], v[46:49]
	v_mfma_f32_16x16x32_bf16 v[42:45], v[138:141], v[198:201], v[42:45]
	v_mfma_f32_16x16x32_bf16 v[42:45], v[142:145], v[202:205], v[42:45]
	v_mfma_f32_16x16x32_bf16 v[38:41], v[146:149], v[198:201], v[38:41]
	v_mfma_f32_16x16x32_bf16 v[38:41], v[150:153], v[202:205], v[38:41]
	v_mfma_f32_16x16x32_bf16 v[34:37], v[174:177], v[198:201], v[34:37]
	v_mfma_f32_16x16x32_bf16 v[34:37], v[178:181], v[202:205], v[34:37]
	v_mfma_f32_16x16x32_bf16 v[30:33], v[130:133], v[206:209], v[30:33]
	v_mfma_f32_16x16x32_bf16 v[30:33], v[134:137], v[210:213], v[30:33]
	v_mfma_f32_16x16x32_bf16 v[26:29], v[138:141], v[206:209], v[26:29]
	v_mfma_f32_16x16x32_bf16 v[26:29], v[142:145], v[210:213], v[26:29]
	v_mfma_f32_16x16x32_bf16 v[22:25], v[146:149], v[206:209], v[22:25]
	v_mfma_f32_16x16x32_bf16 v[22:25], v[150:153], v[210:213], v[22:25]
	v_mfma_f32_16x16x32_bf16 v[18:21], v[174:177], v[206:209], v[18:21]
	v_mfma_f32_16x16x32_bf16 v[18:21], v[178:181], v[210:213], v[18:21]
	v_mfma_f32_16x16x32_bf16 v[14:17], v[130:133], v[214:217], v[14:17]
	v_mfma_f32_16x16x32_bf16 v[14:17], v[134:137], v[218:221], v[14:17]
	v_mfma_f32_16x16x32_bf16 v[10:13], v[138:141], v[214:217], v[10:13]
	v_mfma_f32_16x16x32_bf16 v[10:13], v[142:145], v[218:221], v[10:13]
	v_mfma_f32_16x16x32_bf16 v[6:9], v[146:149], v[214:217], v[6:9]
	v_mfma_f32_16x16x32_bf16 v[6:9], v[150:153], v[218:221], v[6:9]
	v_mfma_f32_16x16x32_bf16 v[2:5], v[174:177], v[214:217], v[2:5]
	v_mfma_f32_16x16x32_bf16 v[2:5], v[178:181], v[218:221], v[2:5]
	s_barrier
	s_add_i32 s72, 0, 0x18000
	s_add_i32 s73, 0, 0x1c000
	ds_read_b128 v[130:133], v246
	ds_read_b128 v[134:137], v246 offset:1024
	ds_read_b128 v[138:141], v246 offset:2048
	ds_read_b128 v[142:145], v246 offset:3072
	ds_read_b128 v[146:149], v247
	ds_read_b128 v[150:153], v247 offset:1024
	ds_read_b128 v[174:177], v247 offset:2048
	ds_read_b128 v[178:181], v247 offset:3072
	s_add_u32 s44, s44, 0x2b0000
	s_addc_u32 s45, s45, 0
	s_mov_b32 m0, s48
	ds_read_b128 v[186:189], v191 offset:32768
	ds_read_b128 v[194:197], v191 offset:33792
	ds_read_b128 v[198:201], v191 offset:34816
	ds_read_b128 v[202:205], v191 offset:35840
	ds_read_b128 v[206:209], v191 offset:36864
	ds_read_b128 v[210:213], v191 offset:37888
	ds_read_b128 v[214:217], v191 offset:38912
	ds_read_b128 v[218:221], v191 offset:39936
	global_load_lds_dwordx4 v154, s[44:45]
	s_mov_b32 m0, s49
	s_nop 0
	global_load_lds_dwordx4 v158, s[44:45]
	s_waitcnt vmcnt(8) lgkmcnt(0)
	s_barrier
	v_mfma_f32_16x16x32_bf16 v[126:129], v[130:133], v[186:189], v[126:129]
	v_mfma_f32_16x16x32_bf16 v[126:129], v[134:137], v[194:197], v[126:129]
	v_mfma_f32_16x16x32_bf16 v[122:125], v[138:141], v[186:189], v[122:125]
	v_mfma_f32_16x16x32_bf16 v[122:125], v[142:145], v[194:197], v[122:125]
	v_mfma_f32_16x16x32_bf16 v[118:121], v[146:149], v[186:189], v[118:121]
	v_mfma_f32_16x16x32_bf16 v[118:121], v[150:153], v[194:197], v[118:121]
	v_mfma_f32_16x16x32_bf16 v[114:117], v[174:177], v[186:189], v[114:117]
	v_mfma_f32_16x16x32_bf16 v[114:117], v[178:181], v[194:197], v[114:117]
	v_mfma_f32_16x16x32_bf16 v[110:113], v[130:133], v[198:201], v[110:113]
	v_mfma_f32_16x16x32_bf16 v[110:113], v[134:137], v[202:205], v[110:113]
	v_mfma_f32_16x16x32_bf16 v[106:109], v[138:141], v[198:201], v[106:109]
	v_mfma_f32_16x16x32_bf16 v[106:109], v[142:145], v[202:205], v[106:109]
	v_mfma_f32_16x16x32_bf16 v[102:105], v[146:149], v[198:201], v[102:105]
	v_mfma_f32_16x16x32_bf16 v[102:105], v[150:153], v[202:205], v[102:105]
	v_mfma_f32_16x16x32_bf16 v[98:101], v[174:177], v[198:201], v[98:101]
	v_mfma_f32_16x16x32_bf16 v[98:101], v[178:181], v[202:205], v[98:101]
	v_mfma_f32_16x16x32_bf16 v[94:97], v[130:133], v[206:209], v[94:97]
	v_mfma_f32_16x16x32_bf16 v[94:97], v[134:137], v[210:213], v[94:97]
	v_mfma_f32_16x16x32_bf16 v[90:93], v[138:141], v[206:209], v[90:93]
	v_mfma_f32_16x16x32_bf16 v[90:93], v[142:145], v[210:213], v[90:93]
	v_mfma_f32_16x16x32_bf16 v[86:89], v[146:149], v[206:209], v[86:89]
	v_mfma_f32_16x16x32_bf16 v[86:89], v[150:153], v[210:213], v[86:89]
	v_mfma_f32_16x16x32_bf16 v[82:85], v[174:177], v[206:209], v[82:85]
	v_mfma_f32_16x16x32_bf16 v[82:85], v[178:181], v[210:213], v[82:85]
	v_mfma_f32_16x16x32_bf16 v[78:81], v[130:133], v[214:217], v[78:81]
	v_mfma_f32_16x16x32_bf16 v[78:81], v[134:137], v[218:221], v[78:81]
	v_mfma_f32_16x16x32_bf16 v[74:77], v[138:141], v[214:217], v[74:77]
	v_mfma_f32_16x16x32_bf16 v[74:77], v[142:145], v[218:221], v[74:77]
	v_mfma_f32_16x16x32_bf16 v[70:73], v[146:149], v[214:217], v[70:73]
	v_mfma_f32_16x16x32_bf16 v[70:73], v[150:153], v[218:221], v[70:73]
	v_mfma_f32_16x16x32_bf16 v[66:69], v[174:177], v[214:217], v[66:69]
	v_mfma_f32_16x16x32_bf16 v[66:69], v[178:181], v[218:221], v[66:69]
	s_barrier
	s_add_i32 s44, s72, s35
	s_mov_b32 m0, s44
	ds_read_b128 v[186:189], v191 offset:49152
	ds_read_b128 v[194:197], v191 offset:50176
	ds_read_b128 v[198:201], v191 offset:51200
	ds_read_b128 v[202:205], v191 offset:52224
	ds_read_b128 v[206:209], v191 offset:53248
	ds_read_b128 v[210:213], v191 offset:54272
	ds_read_b128 v[214:217], v191 offset:55296
	ds_read_b128 v[218:221], v191 offset:56320
	global_load_lds_dwordx4 v156, s[98:99]
	s_add_i32 m0, s44, 0x2000
	s_add_u32 s42, s42, 0x2b0080
	s_addc_u32 s43, s43, 0
	s_add_i32 s44, s73, s35
	global_load_lds_dwordx4 v160, s[98:99]
	s_mov_b32 m0, s44
	s_nop 0
	global_load_lds_dwordx4 v156, s[42:43]
	s_add_i32 m0, s44, 0x2000
	s_nop 0
	global_load_lds_dwordx4 v160, s[42:43]
	s_mov_b32 m0, s51
	s_nop 0
	global_load_lds_dwordx4 v154, s[100:101]
	s_mov_b32 m0, s59
	s_nop 0
	global_load_lds_dwordx4 v158, s[100:101]
	s_waitcnt vmcnt(8) lgkmcnt(0)
	s_barrier
	v_mfma_f32_16x16x32_bf16 v[62:65], v[130:133], v[186:189], v[62:65]
	v_mfma_f32_16x16x32_bf16 v[62:65], v[134:137], v[194:197], v[62:65]
	v_mfma_f32_16x16x32_bf16 v[58:61], v[138:141], v[186:189], v[58:61]
	v_mfma_f32_16x16x32_bf16 v[58:61], v[142:145], v[194:197], v[58:61]
	v_mfma_f32_16x16x32_bf16 v[54:57], v[146:149], v[186:189], v[54:57]
	v_mfma_f32_16x16x32_bf16 v[54:57], v[150:153], v[194:197], v[54:57]
	v_mfma_f32_16x16x32_bf16 v[50:53], v[174:177], v[186:189], v[50:53]
	v_mfma_f32_16x16x32_bf16 v[50:53], v[178:181], v[194:197], v[50:53]
	v_mfma_f32_16x16x32_bf16 v[46:49], v[130:133], v[198:201], v[46:49]
	v_mfma_f32_16x16x32_bf16 v[46:49], v[134:137], v[202:205], v[46:49]
	v_mfma_f32_16x16x32_bf16 v[42:45], v[138:141], v[198:201], v[42:45]
	v_mfma_f32_16x16x32_bf16 v[42:45], v[142:145], v[202:205], v[42:45]
	v_mfma_f32_16x16x32_bf16 v[38:41], v[146:149], v[198:201], v[38:41]
	v_mfma_f32_16x16x32_bf16 v[38:41], v[150:153], v[202:205], v[38:41]
	v_mfma_f32_16x16x32_bf16 v[34:37], v[174:177], v[198:201], v[34:37]
	v_mfma_f32_16x16x32_bf16 v[34:37], v[178:181], v[202:205], v[34:37]
	v_mfma_f32_16x16x32_bf16 v[30:33], v[130:133], v[206:209], v[30:33]
	v_mfma_f32_16x16x32_bf16 v[30:33], v[134:137], v[210:213], v[30:33]
	v_mfma_f32_16x16x32_bf16 v[26:29], v[138:141], v[206:209], v[26:29]
	v_mfma_f32_16x16x32_bf16 v[26:29], v[142:145], v[210:213], v[26:29]
	v_mfma_f32_16x16x32_bf16 v[22:25], v[146:149], v[206:209], v[22:25]
	v_mfma_f32_16x16x32_bf16 v[22:25], v[150:153], v[210:213], v[22:25]
	v_mfma_f32_16x16x32_bf16 v[18:21], v[174:177], v[206:209], v[18:21]
	v_mfma_f32_16x16x32_bf16 v[18:21], v[178:181], v[210:213], v[18:21]
	v_mfma_f32_16x16x32_bf16 v[14:17], v[130:133], v[214:217], v[14:17]
	v_mfma_f32_16x16x32_bf16 v[14:17], v[134:137], v[218:221], v[14:17]
	v_mfma_f32_16x16x32_bf16 v[10:13], v[138:141], v[214:217], v[10:13]
	v_mfma_f32_16x16x32_bf16 v[10:13], v[142:145], v[218:221], v[10:13]
	v_mfma_f32_16x16x32_bf16 v[6:9], v[146:149], v[214:217], v[6:9]
	v_mfma_f32_16x16x32_bf16 v[6:9], v[150:153], v[218:221], v[6:9]
	v_mfma_f32_16x16x32_bf16 v[2:5], v[174:177], v[214:217], v[2:5]
	v_mfma_f32_16x16x32_bf16 v[2:5], v[178:181], v[218:221], v[2:5]
	s_barrier
	s_add_i32 s71, s71, 2
	s_add_u32 s40, s40, 0x100
	s_addc_u32 s41, s41, 0
	s_add_u32 s12, s12, 0x100
	s_addc_u32 s70, s70, 0
	s_cmpk_gt_u32 s71, 0xa9
	s_cbranch_scc0 .LBB0_2340
	s_setprio 0
	s_and_b64 vcc, exec, s[36:37]
	s_cbranch_vccz .LBB0_2343
	s_barrier

.LBB0_2464:
	ds_read_b128 v[150:153], v167
	ds_read_b128 v[172:175], v167 offset:1024
	ds_read_b128 v[176:179], v167 offset:2048
	ds_read_b128 v[184:187], v167 offset:3072
	ds_read_b128 v[188:191], v168
	ds_read_b128 v[192:195], v168 offset:1024
	ds_read_b128 v[196:199], v168 offset:2048
	ds_read_b128 v[200:203], v168 offset:3072
	s_add_u32 s74, s6, 0xfff00080
	s_addc_u32 s75, s7, -1
	s_cmp_eq_u32 s87, 60
	s_cselect_b32 s77, s47, s75
	s_cselect_b32 s76, s83, s74
	s_cselect_b32 s75, s45, s86
	s_cselect_b32 s74, s84, s85
	s_add_i32 m0, s59, 0xc000
	ds_read_b128 v[204:207], v169
	ds_read_b128 v[208:211], v169 offset:1024
	ds_read_b128 v[212:215], v169 offset:2048
	ds_read_b128 v[216:219], v169 offset:3072
	ds_read_b128 v[220:223], v169 offset:4096
	ds_read_b128 v[224:227], v169 offset:5120
	ds_read_b128 v[228:231], v169 offset:6144
	ds_read_b128 v[232:235], v169 offset:7168
	global_load_lds_dwordx4 v142, s[6:7]
	s_add_i32 m0, s59, 0xe000
	s_nop 0
	global_load_lds_dwordx4 v144, s[6:7]
	s_waitcnt vmcnt(8) lgkmcnt(0)
	s_barrier
	v_mfma_f32_16x16x32_bf16 v[126:129], v[150:153], v[204:207], v[126:129]
	v_mfma_f32_16x16x32_bf16 v[126:129], v[172:175], v[208:211], v[126:129]
	v_mfma_f32_16x16x32_bf16 v[122:125], v[176:179], v[204:207], v[122:125]
	v_mfma_f32_16x16x32_bf16 v[122:125], v[184:187], v[208:211], v[122:125]
	v_mfma_f32_16x16x32_bf16 v[118:121], v[188:191], v[204:207], v[118:121]
	v_mfma_f32_16x16x32_bf16 v[118:121], v[192:195], v[208:211], v[118:121]
	v_mfma_f32_16x16x32_bf16 v[114:117], v[196:199], v[204:207], v[114:117]
	v_mfma_f32_16x16x32_bf16 v[114:117], v[200:203], v[208:211], v[114:117]
	v_mfma_f32_16x16x32_bf16 v[110:113], v[150:153], v[212:215], v[110:113]
	v_mfma_f32_16x16x32_bf16 v[110:113], v[172:175], v[216:219], v[110:113]
	v_mfma_f32_16x16x32_bf16 v[106:109], v[176:179], v[212:215], v[106:109]
	v_mfma_f32_16x16x32_bf16 v[106:109], v[184:187], v[216:219], v[106:109]
	v_mfma_f32_16x16x32_bf16 v[102:105], v[188:191], v[212:215], v[102:105]
	v_mfma_f32_16x16x32_bf16 v[102:105], v[192:195], v[216:219], v[102:105]
	v_mfma_f32_16x16x32_bf16 v[98:101], v[196:199], v[212:215], v[98:101]
	v_mfma_f32_16x16x32_bf16 v[98:101], v[200:203], v[216:219], v[98:101]
	v_mfma_f32_16x16x32_bf16 v[94:97], v[150:153], v[220:223], v[94:97]
	v_mfma_f32_16x16x32_bf16 v[94:97], v[172:175], v[224:227], v[94:97]
	v_mfma_f32_16x16x32_bf16 v[90:93], v[176:179], v[220:223], v[90:93]
	v_mfma_f32_16x16x32_bf16 v[90:93], v[184:187], v[224:227], v[90:93]
	v_mfma_f32_16x16x32_bf16 v[86:89], v[188:191], v[220:223], v[86:89]
	v_mfma_f32_16x16x32_bf16 v[86:89], v[192:195], v[224:227], v[86:89]
	v_mfma_f32_16x16x32_bf16 v[82:85], v[196:199], v[220:223], v[82:85]
	v_mfma_f32_16x16x32_bf16 v[82:85], v[200:203], v[224:227], v[82:85]
	v_mfma_f32_16x16x32_bf16 v[78:81], v[150:153], v[228:231], v[78:81]
	v_mfma_f32_16x16x32_bf16 v[78:81], v[172:175], v[232:235], v[78:81]
	v_mfma_f32_16x16x32_bf16 v[74:77], v[176:179], v[228:231], v[74:77]
	v_mfma_f32_16x16x32_bf16 v[74:77], v[184:187], v[232:235], v[74:77]
	v_mfma_f32_16x16x32_bf16 v[70:73], v[188:191], v[228:231], v[70:73]
	v_mfma_f32_16x16x32_bf16 v[70:73], v[192:195], v[232:235], v[70:73]
	v_mfma_f32_16x16x32_bf16 v[66:69], v[196:199], v[228:231], v[66:69]
	v_mfma_f32_16x16x32_bf16 v[66:69], v[200:203], v[232:235], v[66:69]
	s_barrier
	s_add_i32 s88, s70, s27
	s_add_u32 s98, s74, 0x80
	s_addc_u32 s99, s75, 0
	s_mov_b32 m0, s88
	ds_read_b128 v[204:207], v169 offset:16384
	ds_read_b128 v[208:211], v169 offset:17408
	ds_read_b128 v[212:215], v169 offset:18432
	ds_read_b128 v[216:219], v169 offset:19456
	ds_read_b128 v[220:223], v169 offset:20480
	ds_read_b128 v[224:227], v169 offset:21504
	ds_read_b128 v[228:231], v169 offset:22528
	ds_read_b128 v[232:235], v169 offset:23552
	global_load_lds_dwordx4 v132, s[74:75]
	s_add_i32 m0, s88, 0x2000
	s_add_u32 s88, s74, 0x100000
	s_addc_u32 s89, s75, 0
	s_add_i32 s90, s71, s27
	global_load_lds_dwordx4 v136, s[74:75]
	s_mov_b32 m0, s90
	global_load_lds_dwordx4 v132, s[88:89]
	s_add_i32 m0, s90, 0x2000
	s_nop 0
	global_load_lds_dwordx4 v136, s[88:89]
	s_add_u32 s100, s76, 0x80
	s_addc_u32 s101, s77, 0
	s_mov_b32 m0, s59
	s_nop 0
	global_load_lds_dwordx4 v130, s[76:77]
	s_mov_b32 m0, s62
	s_nop 0
	global_load_lds_dwordx4 v134, s[76:77]
	s_waitcnt vmcnt(8) lgkmcnt(0)
	s_barrier
	v_mfma_f32_16x16x32_bf16 v[62:65], v[150:153], v[204:207], v[62:65]
	v_mfma_f32_16x16x32_bf16 v[62:65], v[172:175], v[208:211], v[62:65]
	v_mfma_f32_16x16x32_bf16 v[58:61], v[176:179], v[204:207], v[58:61]
	v_mfma_f32_16x16x32_bf16 v[58:61], v[184:187], v[208:211], v[58:61]
	v_mfma_f32_16x16x32_bf16 v[54:57], v[188:191], v[204:207], v[54:57]
	v_mfma_f32_16x16x32_bf16 v[54:57], v[192:195], v[208:211], v[54:57]
	v_mfma_f32_16x16x32_bf16 v[46:49], v[196:199], v[204:207], v[46:49]
	v_mfma_f32_16x16x32_bf16 v[46:49], v[200:203], v[208:211], v[46:49]
	v_mfma_f32_16x16x32_bf16 v[50:53], v[150:153], v[212:215], v[50:53]
	v_mfma_f32_16x16x32_bf16 v[50:53], v[172:175], v[216:219], v[50:53]
	v_mfma_f32_16x16x32_bf16 v[42:45], v[176:179], v[212:215], v[42:45]
	v_mfma_f32_16x16x32_bf16 v[42:45], v[184:187], v[216:219], v[42:45]
	v_mfma_f32_16x16x32_bf16 v[38:41], v[188:191], v[212:215], v[38:41]
	v_mfma_f32_16x16x32_bf16 v[38:41], v[192:195], v[216:219], v[38:41]
	v_mfma_f32_16x16x32_bf16 v[30:33], v[196:199], v[212:215], v[30:33]
	v_mfma_f32_16x16x32_bf16 v[30:33], v[200:203], v[216:219], v[30:33]
	v_mfma_f32_16x16x32_bf16 v[34:37], v[150:153], v[220:223], v[34:37]
	v_mfma_f32_16x16x32_bf16 v[34:37], v[172:175], v[224:227], v[34:37]
	v_mfma_f32_16x16x32_bf16 v[26:29], v[176:179], v[220:223], v[26:29]
	v_mfma_f32_16x16x32_bf16 v[26:29], v[184:187], v[224:227], v[26:29]
	v_mfma_f32_16x16x32_bf16 v[22:25], v[188:191], v[220:223], v[22:25]
	v_mfma_f32_16x16x32_bf16 v[22:25], v[192:195], v[224:227], v[22:25]
	v_mfma_f32_16x16x32_bf16 v[14:17], v[196:199], v[220:223], v[14:17]
	v_mfma_f32_16x16x32_bf16 v[14:17], v[200:203], v[224:227], v[14:17]
	v_mfma_f32_16x16x32_bf16 v[18:21], v[150:153], v[228:231], v[18:21]
	v_mfma_f32_16x16x32_bf16 v[18:21], v[172:175], v[232:235], v[18:21]
	v_mfma_f32_16x16x32_bf16 v[10:13], v[176:179], v[228:231], v[10:13]
	v_mfma_f32_16x16x32_bf16 v[10:13], v[184:187], v[232:235], v[10:13]
	v_mfma_f32_16x16x32_bf16 v[6:9], v[188:191], v[228:231], v[6:9]
	v_mfma_f32_16x16x32_bf16 v[6:9], v[192:195], v[232:235], v[6:9]
	v_mfma_f32_16x16x32_bf16 v[2:5], v[196:199], v[228:231], v[2:5]
	v_mfma_f32_16x16x32_bf16 v[2:5], v[200:203], v[232:235], v[2:5]
	s_barrier
	s_add_i32 s88, 0, 0x18000
	s_add_i32 s89, 0, 0x1c000
	ds_read_b128 v[150:153], v246
	ds_read_b128 v[172:175], v246 offset:1024
	ds_read_b128 v[176:179], v246 offset:2048
	ds_read_b128 v[184:187], v246 offset:3072
	ds_read_b128 v[188:191], v247
	ds_read_b128 v[192:195], v247 offset:1024
	ds_read_b128 v[196:199], v247 offset:2048
	ds_read_b128 v[200:203], v247 offset:3072
	s_add_u32 s76, s76, 0x100000
	s_addc_u32 s77, s77, 0
	s_mov_b32 m0, s63
	ds_read_b128 v[204:207], v169 offset:32768
	ds_read_b128 v[208:211], v169 offset:33792
	ds_read_b128 v[212:215], v169 offset:34816
	ds_read_b128 v[216:219], v169 offset:35840
	ds_read_b128 v[220:223], v169 offset:36864
	ds_read_b128 v[224:227], v169 offset:37888
	ds_read_b128 v[228:231], v169 offset:38912
	ds_read_b128 v[232:235], v169 offset:39936
	global_load_lds_dwordx4 v130, s[76:77]
	s_mov_b32 m0, s65
	s_nop 0
	global_load_lds_dwordx4 v134, s[76:77]
	s_waitcnt vmcnt(8) lgkmcnt(0)
	s_barrier
	v_mfma_f32_16x16x32_bf16 v[126:129], v[150:153], v[204:207], v[126:129]
	v_mfma_f32_16x16x32_bf16 v[126:129], v[172:175], v[208:211], v[126:129]
	v_mfma_f32_16x16x32_bf16 v[122:125], v[176:179], v[204:207], v[122:125]
	v_mfma_f32_16x16x32_bf16 v[122:125], v[184:187], v[208:211], v[122:125]
	v_mfma_f32_16x16x32_bf16 v[118:121], v[188:191], v[204:207], v[118:121]
	v_mfma_f32_16x16x32_bf16 v[118:121], v[192:195], v[208:211], v[118:121]
	v_mfma_f32_16x16x32_bf16 v[114:117], v[196:199], v[204:207], v[114:117]
	v_mfma_f32_16x16x32_bf16 v[114:117], v[200:203], v[208:211], v[114:117]
	v_mfma_f32_16x16x32_bf16 v[110:113], v[150:153], v[212:215], v[110:113]
	v_mfma_f32_16x16x32_bf16 v[110:113], v[172:175], v[216:219], v[110:113]
	v_mfma_f32_16x16x32_bf16 v[106:109], v[176:179], v[212:215], v[106:109]
	v_mfma_f32_16x16x32_bf16 v[106:109], v[184:187], v[216:219], v[106:109]
	v_mfma_f32_16x16x32_bf16 v[102:105], v[188:191], v[212:215], v[102:105]
	v_mfma_f32_16x16x32_bf16 v[102:105], v[192:195], v[216:219], v[102:105]
	v_mfma_f32_16x16x32_bf16 v[98:101], v[196:199], v[212:215], v[98:101]
	v_mfma_f32_16x16x32_bf16 v[98:101], v[200:203], v[216:219], v[98:101]
	v_mfma_f32_16x16x32_bf16 v[94:97], v[150:153], v[220:223], v[94:97]
	v_mfma_f32_16x16x32_bf16 v[94:97], v[172:175], v[224:227], v[94:97]
	v_mfma_f32_16x16x32_bf16 v[90:93], v[176:179], v[220:223], v[90:93]
	v_mfma_f32_16x16x32_bf16 v[90:93], v[184:187], v[224:227], v[90:93]
	v_mfma_f32_16x16x32_bf16 v[86:89], v[188:191], v[220:223], v[86:89]
	v_mfma_f32_16x16x32_bf16 v[86:89], v[192:195], v[224:227], v[86:89]
	v_mfma_f32_16x16x32_bf16 v[82:85], v[196:199], v[220:223], v[82:85]
	v_mfma_f32_16x16x32_bf16 v[82:85], v[200:203], v[224:227], v[82:85]
	v_mfma_f32_16x16x32_bf16 v[78:81], v[150:153], v[228:231], v[78:81]
	v_mfma_f32_16x16x32_bf16 v[78:81], v[172:175], v[232:235], v[78:81]
	v_mfma_f32_16x16x32_bf16 v[74:77], v[176:179], v[228:231], v[74:77]
	v_mfma_f32_16x16x32_bf16 v[74:77], v[184:187], v[232:235], v[74:77]
	v_mfma_f32_16x16x32_bf16 v[70:73], v[188:191], v[228:231], v[70:73]
	v_mfma_f32_16x16x32_bf16 v[70:73], v[192:195], v[232:235], v[70:73]
	v_mfma_f32_16x16x32_bf16 v[66:69], v[196:199], v[228:231], v[66:69]
	v_mfma_f32_16x16x32_bf16 v[66:69], v[200:203], v[232:235], v[66:69]
	s_barrier
	s_add_i32 s76, s88, s27
	s_mov_b32 m0, s76
	ds_read_b128 v[204:207], v169 offset:49152
	ds_read_b128 v[208:211], v169 offset:50176
	ds_read_b128 v[212:215], v169 offset:51200
	ds_read_b128 v[216:219], v169 offset:52224
	ds_read_b128 v[220:223], v169 offset:53248
	ds_read_b128 v[224:227], v169 offset:54272
	ds_read_b128 v[228:231], v169 offset:55296
	ds_read_b128 v[232:235], v169 offset:56320
	global_load_lds_dwordx4 v132, s[98:99]
	s_add_i32 m0, s76, 0x2000
	s_add_u32 s74, s74, 0x100080
	s_addc_u32 s75, s75, 0
	s_add_i32 s76, s89, s27
	global_load_lds_dwordx4 v136, s[98:99]
	s_mov_b32 m0, s76
	s_nop 0
	global_load_lds_dwordx4 v132, s[74:75]
	s_add_i32 m0, s76, 0x2000
	s_nop 0
	global_load_lds_dwordx4 v136, s[74:75]
	s_mov_b32 m0, s67
	s_nop 0
	global_load_lds_dwordx4 v130, s[100:101]
	s_mov_b32 m0, s68
	s_nop 0
	global_load_lds_dwordx4 v134, s[100:101]
	s_waitcnt vmcnt(8) lgkmcnt(0)
	s_barrier
	v_mfma_f32_16x16x32_bf16 v[62:65], v[150:153], v[204:207], v[62:65]
	v_mfma_f32_16x16x32_bf16 v[62:65], v[172:175], v[208:211], v[62:65]
	v_mfma_f32_16x16x32_bf16 v[58:61], v[176:179], v[204:207], v[58:61]
	v_mfma_f32_16x16x32_bf16 v[58:61], v[184:187], v[208:211], v[58:61]
	v_mfma_f32_16x16x32_bf16 v[54:57], v[188:191], v[204:207], v[54:57]
	v_mfma_f32_16x16x32_bf16 v[54:57], v[192:195], v[208:211], v[54:57]
	v_mfma_f32_16x16x32_bf16 v[46:49], v[196:199], v[204:207], v[46:49]
	v_mfma_f32_16x16x32_bf16 v[46:49], v[200:203], v[208:211], v[46:49]
	v_mfma_f32_16x16x32_bf16 v[50:53], v[150:153], v[212:215], v[50:53]
	v_mfma_f32_16x16x32_bf16 v[50:53], v[172:175], v[216:219], v[50:53]
	v_mfma_f32_16x16x32_bf16 v[42:45], v[176:179], v[212:215], v[42:45]
	v_mfma_f32_16x16x32_bf16 v[42:45], v[184:187], v[216:219], v[42:45]
	v_mfma_f32_16x16x32_bf16 v[38:41], v[188:191], v[212:215], v[38:41]
	v_mfma_f32_16x16x32_bf16 v[38:41], v[192:195], v[216:219], v[38:41]
	v_mfma_f32_16x16x32_bf16 v[30:33], v[196:199], v[212:215], v[30:33]
	v_mfma_f32_16x16x32_bf16 v[30:33], v[200:203], v[216:219], v[30:33]
	v_mfma_f32_16x16x32_bf16 v[34:37], v[150:153], v[220:223], v[34:37]
	v_mfma_f32_16x16x32_bf16 v[34:37], v[172:175], v[224:227], v[34:37]
	v_mfma_f32_16x16x32_bf16 v[26:29], v[176:179], v[220:223], v[26:29]
	v_mfma_f32_16x16x32_bf16 v[26:29], v[184:187], v[224:227], v[26:29]
	v_mfma_f32_16x16x32_bf16 v[22:25], v[188:191], v[220:223], v[22:25]
	v_mfma_f32_16x16x32_bf16 v[22:25], v[192:195], v[224:227], v[22:25]
	v_mfma_f32_16x16x32_bf16 v[14:17], v[196:199], v[220:223], v[14:17]
	v_mfma_f32_16x16x32_bf16 v[14:17], v[200:203], v[224:227], v[14:17]
	v_mfma_f32_16x16x32_bf16 v[18:21], v[150:153], v[228:231], v[18:21]
	v_mfma_f32_16x16x32_bf16 v[18:21], v[172:175], v[232:235], v[18:21]
	v_mfma_f32_16x16x32_bf16 v[10:13], v[176:179], v[228:231], v[10:13]
	v_mfma_f32_16x16x32_bf16 v[10:13], v[184:187], v[232:235], v[10:13]
	v_mfma_f32_16x16x32_bf16 v[6:9], v[188:191], v[228:231], v[6:9]
	v_mfma_f32_16x16x32_bf16 v[6:9], v[192:195], v[232:235], v[6:9]
	v_mfma_f32_16x16x32_bf16 v[2:5], v[196:199], v[228:231], v[2:5]
	v_mfma_f32_16x16x32_bf16 v[2:5], v[200:203], v[232:235], v[2:5]
	s_barrier
	s_add_i32 s87, s87, 2
	s_add_u32 s6, s6, 0x100
	s_addc_u32 s7, s7, 0
	s_add_u32 s85, s85, 0x100
	s_addc_u32 s86, s86, 0
	s_cmp_gt_u32 s87, 61
	s_cbranch_scc0 .LBB0_2464
	s_setprio 0
	s_and_b64 vcc, exec, s[38:39]
	s_cbranch_vccz .LBB0_2467
	s_barrier

.LBB0_2494:
	ds_read_b128 v[160:163], v155
	ds_read_b128 v[164:167], v155 offset:1024
	ds_read_b128 v[168:171], v155 offset:2048
	ds_read_b128 v[172:175], v155 offset:3072
	ds_read_b128 v[176:179], v156
	ds_read_b128 v[184:187], v156 offset:1024
	ds_read_b128 v[188:191], v156 offset:2048
	ds_read_b128 v[192:195], v156 offset:3072
	s_add_u32 s48, s6, 0xfff00080
	s_addc_u32 s49, s7, -1
	s_cmp_eq_u32 s89, 60
	s_cselect_b32 s51, s43, s49
	s_cselect_b32 s50, s85, s48
	s_cselect_b32 s49, s41, s88
	s_cselect_b32 s48, s86, s87
	s_add_i32 m0, s63, 0xc000
	ds_read_b128 v[196:199], v157
	ds_read_b128 v[200:203], v157 offset:1024
	ds_read_b128 v[204:207], v157 offset:2048
	ds_read_b128 v[208:211], v157 offset:3072
	ds_read_b128 v[212:215], v157 offset:4096
	ds_read_b128 v[216:219], v157 offset:5120
	ds_read_b128 v[220:223], v157 offset:6144
	ds_read_b128 v[224:227], v157 offset:7168
	global_load_lds_dwordx4 v140, s[6:7]
	s_add_i32 m0, s63, 0xe000
	s_nop 0
	global_load_lds_dwordx4 v142, s[6:7]
	s_waitcnt vmcnt(8) lgkmcnt(0)
	s_barrier
	v_mfma_f32_16x16x32_bf16 v[126:129], v[160:163], v[196:199], v[126:129]
	v_mfma_f32_16x16x32_bf16 v[126:129], v[164:167], v[200:203], v[126:129]
	v_mfma_f32_16x16x32_bf16 v[122:125], v[168:171], v[196:199], v[122:125]
	v_mfma_f32_16x16x32_bf16 v[122:125], v[172:175], v[200:203], v[122:125]
	v_mfma_f32_16x16x32_bf16 v[118:121], v[176:179], v[196:199], v[118:121]
	v_mfma_f32_16x16x32_bf16 v[118:121], v[184:187], v[200:203], v[118:121]
	v_mfma_f32_16x16x32_bf16 v[114:117], v[188:191], v[196:199], v[114:117]
	v_mfma_f32_16x16x32_bf16 v[114:117], v[192:195], v[200:203], v[114:117]
	v_mfma_f32_16x16x32_bf16 v[110:113], v[160:163], v[204:207], v[110:113]
	v_mfma_f32_16x16x32_bf16 v[110:113], v[164:167], v[208:211], v[110:113]
	v_mfma_f32_16x16x32_bf16 v[106:109], v[168:171], v[204:207], v[106:109]
	v_mfma_f32_16x16x32_bf16 v[106:109], v[172:175], v[208:211], v[106:109]
	v_mfma_f32_16x16x32_bf16 v[102:105], v[176:179], v[204:207], v[102:105]
	v_mfma_f32_16x16x32_bf16 v[102:105], v[184:187], v[208:211], v[102:105]
	v_mfma_f32_16x16x32_bf16 v[98:101], v[188:191], v[204:207], v[98:101]
	v_mfma_f32_16x16x32_bf16 v[98:101], v[192:195], v[208:211], v[98:101]
	v_mfma_f32_16x16x32_bf16 v[94:97], v[160:163], v[212:215], v[94:97]
	v_mfma_f32_16x16x32_bf16 v[94:97], v[164:167], v[216:219], v[94:97]
	v_mfma_f32_16x16x32_bf16 v[90:93], v[168:171], v[212:215], v[90:93]
	v_mfma_f32_16x16x32_bf16 v[90:93], v[172:175], v[216:219], v[90:93]
	v_mfma_f32_16x16x32_bf16 v[86:89], v[176:179], v[212:215], v[86:89]
	v_mfma_f32_16x16x32_bf16 v[86:89], v[184:187], v[216:219], v[86:89]
	v_mfma_f32_16x16x32_bf16 v[82:85], v[188:191], v[212:215], v[82:85]
	v_mfma_f32_16x16x32_bf16 v[82:85], v[192:195], v[216:219], v[82:85]
	v_mfma_f32_16x16x32_bf16 v[78:81], v[160:163], v[220:223], v[78:81]
	v_mfma_f32_16x16x32_bf16 v[78:81], v[164:167], v[224:227], v[78:81]
	v_mfma_f32_16x16x32_bf16 v[74:77], v[168:171], v[220:223], v[74:77]
	v_mfma_f32_16x16x32_bf16 v[74:77], v[172:175], v[224:227], v[74:77]
	v_mfma_f32_16x16x32_bf16 v[70:73], v[176:179], v[220:223], v[70:73]
	v_mfma_f32_16x16x32_bf16 v[70:73], v[184:187], v[224:227], v[70:73]
	v_mfma_f32_16x16x32_bf16 v[66:69], v[188:191], v[220:223], v[66:69]
	v_mfma_f32_16x16x32_bf16 v[66:69], v[192:195], v[224:227], v[66:69]
	s_barrier
	s_add_i32 s90, s73, s27
	s_add_u32 s98, s48, 0x80
	s_addc_u32 s99, s49, 0
	s_mov_b32 m0, s90
	ds_read_b128 v[196:199], v157 offset:16384
	ds_read_b128 v[200:203], v157 offset:17408
	ds_read_b128 v[204:207], v157 offset:18432
	ds_read_b128 v[208:211], v157 offset:19456
	ds_read_b128 v[212:215], v157 offset:20480
	ds_read_b128 v[216:219], v157 offset:21504
	ds_read_b128 v[220:223], v157 offset:22528
	ds_read_b128 v[224:227], v157 offset:23552
	global_load_lds_dwordx4 v132, s[48:49]
	s_add_i32 m0, s90, 0x2000
	s_add_u32 s90, s48, 0x100000
	s_addc_u32 s91, s49, 0
	s_add_i32 s92, s74, s27
	global_load_lds_dwordx4 v136, s[48:49]
	s_mov_b32 m0, s92
	global_load_lds_dwordx4 v132, s[90:91]
	s_add_i32 m0, s92, 0x2000
	s_nop 0
	global_load_lds_dwordx4 v136, s[90:91]
	s_add_u32 s100, s50, 0x80
	s_addc_u32 s101, s51, 0
	s_mov_b32 m0, s63
	s_nop 0
	global_load_lds_dwordx4 v130, s[50:51]
	s_mov_b32 m0, s65
	s_nop 0
	global_load_lds_dwordx4 v134, s[50:51]
	s_waitcnt vmcnt(8) lgkmcnt(0)
	s_barrier
	v_mfma_f32_16x16x32_bf16 v[62:65], v[160:163], v[196:199], v[62:65]
	v_mfma_f32_16x16x32_bf16 v[62:65], v[164:167], v[200:203], v[62:65]
	v_mfma_f32_16x16x32_bf16 v[58:61], v[168:171], v[196:199], v[58:61]
	v_mfma_f32_16x16x32_bf16 v[58:61], v[172:175], v[200:203], v[58:61]
	v_mfma_f32_16x16x32_bf16 v[54:57], v[176:179], v[196:199], v[54:57]
	v_mfma_f32_16x16x32_bf16 v[54:57], v[184:187], v[200:203], v[54:57]
	v_mfma_f32_16x16x32_bf16 v[46:49], v[188:191], v[196:199], v[46:49]
	v_mfma_f32_16x16x32_bf16 v[46:49], v[192:195], v[200:203], v[46:49]
	v_mfma_f32_16x16x32_bf16 v[50:53], v[160:163], v[204:207], v[50:53]
	v_mfma_f32_16x16x32_bf16 v[50:53], v[164:167], v[208:211], v[50:53]
	v_mfma_f32_16x16x32_bf16 v[42:45], v[168:171], v[204:207], v[42:45]
	v_mfma_f32_16x16x32_bf16 v[42:45], v[172:175], v[208:211], v[42:45]
	v_mfma_f32_16x16x32_bf16 v[38:41], v[176:179], v[204:207], v[38:41]
	v_mfma_f32_16x16x32_bf16 v[38:41], v[184:187], v[208:211], v[38:41]
	v_mfma_f32_16x16x32_bf16 v[30:33], v[188:191], v[204:207], v[30:33]
	v_mfma_f32_16x16x32_bf16 v[30:33], v[192:195], v[208:211], v[30:33]
	v_mfma_f32_16x16x32_bf16 v[34:37], v[160:163], v[212:215], v[34:37]
	v_mfma_f32_16x16x32_bf16 v[34:37], v[164:167], v[216:219], v[34:37]
	v_mfma_f32_16x16x32_bf16 v[26:29], v[168:171], v[212:215], v[26:29]
	v_mfma_f32_16x16x32_bf16 v[26:29], v[172:175], v[216:219], v[26:29]
	v_mfma_f32_16x16x32_bf16 v[22:25], v[176:179], v[212:215], v[22:25]
	v_mfma_f32_16x16x32_bf16 v[22:25], v[184:187], v[216:219], v[22:25]
	v_mfma_f32_16x16x32_bf16 v[14:17], v[188:191], v[212:215], v[14:17]
	v_mfma_f32_16x16x32_bf16 v[14:17], v[192:195], v[216:219], v[14:17]
	v_mfma_f32_16x16x32_bf16 v[18:21], v[160:163], v[220:223], v[18:21]
	v_mfma_f32_16x16x32_bf16 v[18:21], v[164:167], v[224:227], v[18:21]
	v_mfma_f32_16x16x32_bf16 v[10:13], v[168:171], v[220:223], v[10:13]
	v_mfma_f32_16x16x32_bf16 v[10:13], v[172:175], v[224:227], v[10:13]
	v_mfma_f32_16x16x32_bf16 v[6:9], v[176:179], v[220:223], v[6:9]
	v_mfma_f32_16x16x32_bf16 v[6:9], v[184:187], v[224:227], v[6:9]
	v_mfma_f32_16x16x32_bf16 v[2:5], v[188:191], v[220:223], v[2:5]
	v_mfma_f32_16x16x32_bf16 v[2:5], v[192:195], v[224:227], v[2:5]
	s_barrier
	s_add_i32 s90, 0, 0x18000
	s_add_i32 s91, 0, 0x1c000
	ds_read_b128 v[160:163], v246
	ds_read_b128 v[164:167], v246 offset:1024
	ds_read_b128 v[168:171], v246 offset:2048
	ds_read_b128 v[172:175], v246 offset:3072
	ds_read_b128 v[176:179], v247
	ds_read_b128 v[184:187], v247 offset:1024
	ds_read_b128 v[188:191], v247 offset:2048
	ds_read_b128 v[192:195], v247 offset:3072
	s_add_u32 s50, s50, 0x100000
	s_addc_u32 s51, s51, 0
	s_mov_b32 m0, s66
	ds_read_b128 v[196:199], v157 offset:32768
	ds_read_b128 v[200:203], v157 offset:33792
	ds_read_b128 v[204:207], v157 offset:34816
	ds_read_b128 v[208:211], v157 offset:35840
	ds_read_b128 v[212:215], v157 offset:36864
	ds_read_b128 v[216:219], v157 offset:37888
	ds_read_b128 v[220:223], v157 offset:38912
	ds_read_b128 v[224:227], v157 offset:39936
	global_load_lds_dwordx4 v130, s[50:51]
	s_mov_b32 m0, s67
	s_nop 0
	global_load_lds_dwordx4 v134, s[50:51]
	s_waitcnt vmcnt(8) lgkmcnt(0)
	s_barrier
	v_mfma_f32_16x16x32_bf16 v[126:129], v[160:163], v[196:199], v[126:129]
	v_mfma_f32_16x16x32_bf16 v[126:129], v[164:167], v[200:203], v[126:129]
	v_mfma_f32_16x16x32_bf16 v[122:125], v[168:171], v[196:199], v[122:125]
	v_mfma_f32_16x16x32_bf16 v[122:125], v[172:175], v[200:203], v[122:125]
	v_mfma_f32_16x16x32_bf16 v[118:121], v[176:179], v[196:199], v[118:121]
	v_mfma_f32_16x16x32_bf16 v[118:121], v[184:187], v[200:203], v[118:121]
	v_mfma_f32_16x16x32_bf16 v[114:117], v[188:191], v[196:199], v[114:117]
	v_mfma_f32_16x16x32_bf16 v[114:117], v[192:195], v[200:203], v[114:117]
	v_mfma_f32_16x16x32_bf16 v[110:113], v[160:163], v[204:207], v[110:113]
	v_mfma_f32_16x16x32_bf16 v[110:113], v[164:167], v[208:211], v[110:113]
	v_mfma_f32_16x16x32_bf16 v[106:109], v[168:171], v[204:207], v[106:109]
	v_mfma_f32_16x16x32_bf16 v[106:109], v[172:175], v[208:211], v[106:109]
	v_mfma_f32_16x16x32_bf16 v[102:105], v[176:179], v[204:207], v[102:105]
	v_mfma_f32_16x16x32_bf16 v[102:105], v[184:187], v[208:211], v[102:105]
	v_mfma_f32_16x16x32_bf16 v[98:101], v[188:191], v[204:207], v[98:101]
	v_mfma_f32_16x16x32_bf16 v[98:101], v[192:195], v[208:211], v[98:101]
	v_mfma_f32_16x16x32_bf16 v[94:97], v[160:163], v[212:215], v[94:97]
	v_mfma_f32_16x16x32_bf16 v[94:97], v[164:167], v[216:219], v[94:97]
	v_mfma_f32_16x16x32_bf16 v[90:93], v[168:171], v[212:215], v[90:93]
	v_mfma_f32_16x16x32_bf16 v[90:93], v[172:175], v[216:219], v[90:93]
	v_mfma_f32_16x16x32_bf16 v[86:89], v[176:179], v[212:215], v[86:89]
	v_mfma_f32_16x16x32_bf16 v[86:89], v[184:187], v[216:219], v[86:89]
	v_mfma_f32_16x16x32_bf16 v[82:85], v[188:191], v[212:215], v[82:85]
	v_mfma_f32_16x16x32_bf16 v[82:85], v[192:195], v[216:219], v[82:85]
	v_mfma_f32_16x16x32_bf16 v[78:81], v[160:163], v[220:223], v[78:81]
	v_mfma_f32_16x16x32_bf16 v[78:81], v[164:167], v[224:227], v[78:81]
	v_mfma_f32_16x16x32_bf16 v[74:77], v[168:171], v[220:223], v[74:77]
	v_mfma_f32_16x16x32_bf16 v[74:77], v[172:175], v[224:227], v[74:77]
	v_mfma_f32_16x16x32_bf16 v[70:73], v[176:179], v[220:223], v[70:73]
	v_mfma_f32_16x16x32_bf16 v[70:73], v[184:187], v[224:227], v[70:73]
	v_mfma_f32_16x16x32_bf16 v[66:69], v[188:191], v[220:223], v[66:69]
	v_mfma_f32_16x16x32_bf16 v[66:69], v[192:195], v[224:227], v[66:69]
	s_barrier
	s_add_i32 s50, s90, s27
	s_mov_b32 m0, s50
	ds_read_b128 v[196:199], v157 offset:49152
	ds_read_b128 v[200:203], v157 offset:50176
	ds_read_b128 v[204:207], v157 offset:51200
	ds_read_b128 v[208:211], v157 offset:52224
	ds_read_b128 v[212:215], v157 offset:53248
	ds_read_b128 v[216:219], v157 offset:54272
	ds_read_b128 v[220:223], v157 offset:55296
	ds_read_b128 v[224:227], v157 offset:56320
	global_load_lds_dwordx4 v132, s[98:99]
	s_add_i32 m0, s50, 0x2000
	s_add_u32 s48, s48, 0x100080
	s_addc_u32 s49, s49, 0
	s_add_i32 s50, s91, s27
	global_load_lds_dwordx4 v136, s[98:99]
	s_mov_b32 m0, s50
	s_nop 0
	global_load_lds_dwordx4 v132, s[48:49]
	s_add_i32 m0, s50, 0x2000
	s_nop 0
	global_load_lds_dwordx4 v136, s[48:49]
	s_mov_b32 m0, s69
	s_nop 0
	global_load_lds_dwordx4 v130, s[100:101]
	s_mov_b32 m0, s70
	s_nop 0
	global_load_lds_dwordx4 v134, s[100:101]
	s_waitcnt vmcnt(8) lgkmcnt(0)
	s_barrier
	v_mfma_f32_16x16x32_bf16 v[62:65], v[160:163], v[196:199], v[62:65]
	v_mfma_f32_16x16x32_bf16 v[62:65], v[164:167], v[200:203], v[62:65]
	v_mfma_f32_16x16x32_bf16 v[58:61], v[168:171], v[196:199], v[58:61]
	v_mfma_f32_16x16x32_bf16 v[58:61], v[172:175], v[200:203], v[58:61]
	v_mfma_f32_16x16x32_bf16 v[54:57], v[176:179], v[196:199], v[54:57]
	v_mfma_f32_16x16x32_bf16 v[54:57], v[184:187], v[200:203], v[54:57]
	v_mfma_f32_16x16x32_bf16 v[46:49], v[188:191], v[196:199], v[46:49]
	v_mfma_f32_16x16x32_bf16 v[46:49], v[192:195], v[200:203], v[46:49]
	v_mfma_f32_16x16x32_bf16 v[50:53], v[160:163], v[204:207], v[50:53]
	v_mfma_f32_16x16x32_bf16 v[50:53], v[164:167], v[208:211], v[50:53]
	v_mfma_f32_16x16x32_bf16 v[42:45], v[168:171], v[204:207], v[42:45]
	v_mfma_f32_16x16x32_bf16 v[42:45], v[172:175], v[208:211], v[42:45]
	v_mfma_f32_16x16x32_bf16 v[38:41], v[176:179], v[204:207], v[38:41]
	v_mfma_f32_16x16x32_bf16 v[38:41], v[184:187], v[208:211], v[38:41]
	v_mfma_f32_16x16x32_bf16 v[30:33], v[188:191], v[204:207], v[30:33]
	v_mfma_f32_16x16x32_bf16 v[30:33], v[192:195], v[208:211], v[30:33]
	v_mfma_f32_16x16x32_bf16 v[34:37], v[160:163], v[212:215], v[34:37]
	v_mfma_f32_16x16x32_bf16 v[34:37], v[164:167], v[216:219], v[34:37]
	v_mfma_f32_16x16x32_bf16 v[26:29], v[168:171], v[212:215], v[26:29]
	v_mfma_f32_16x16x32_bf16 v[26:29], v[172:175], v[216:219], v[26:29]
	v_mfma_f32_16x16x32_bf16 v[22:25], v[176:179], v[212:215], v[22:25]
	v_mfma_f32_16x16x32_bf16 v[22:25], v[184:187], v[216:219], v[22:25]
	v_mfma_f32_16x16x32_bf16 v[14:17], v[188:191], v[212:215], v[14:17]
	v_mfma_f32_16x16x32_bf16 v[14:17], v[192:195], v[216:219], v[14:17]
	v_mfma_f32_16x16x32_bf16 v[18:21], v[160:163], v[220:223], v[18:21]
	v_mfma_f32_16x16x32_bf16 v[18:21], v[164:167], v[224:227], v[18:21]
	v_mfma_f32_16x16x32_bf16 v[10:13], v[168:171], v[220:223], v[10:13]
	v_mfma_f32_16x16x32_bf16 v[10:13], v[172:175], v[224:227], v[10:13]
	v_mfma_f32_16x16x32_bf16 v[6:9], v[176:179], v[220:223], v[6:9]
	v_mfma_f32_16x16x32_bf16 v[6:9], v[184:187], v[224:227], v[6:9]
	v_mfma_f32_16x16x32_bf16 v[2:5], v[188:191], v[220:223], v[2:5]
	v_mfma_f32_16x16x32_bf16 v[2:5], v[192:195], v[224:227], v[2:5]
	s_barrier
	s_add_i32 s89, s89, 2
	s_add_u32 s6, s6, 0x100
	s_addc_u32 s7, s7, 0
	s_add_u32 s87, s87, 0x100
	s_addc_u32 s88, s88, 0
	s_cmp_gt_u32 s89, 61
	s_cbranch_scc0 .LBB0_2494
	s_setprio 0
	s_and_b64 vcc, exec, s[38:39]
	s_cbranch_vccz .LBB0_2497
	s_barrier

.LBB0_2635:
	ds_read_b128 v[130:133], v163
	ds_read_b128 v[134:137], v163 offset:1024
	ds_read_b128 v[138:141], v163 offset:2048
	ds_read_b128 v[142:145], v163 offset:3072
	ds_read_b128 v[146:149], v188
	ds_read_b128 v[150:153], v188 offset:1024
	ds_read_b128 v[174:177], v188 offset:2048
	ds_read_b128 v[178:181], v188 offset:3072
	s_add_u32 s48, s46, 0xfff00080
	s_addc_u32 s49, s47, -1
	s_cmp_eq_u32 s73, 60
	s_cselect_b32 s51, s22, s49
	s_cselect_b32 s50, s41, s48
	s_cselect_b32 s49, s39, s72
	s_cselect_b32 s48, s70, s71
	s_add_i32 m0, s13, 0xc000
	ds_read_b128 v[184:187], v189
	ds_read_b128 v[192:195], v189 offset:1024
	ds_read_b128 v[196:199], v189 offset:2048
	ds_read_b128 v[200:203], v189 offset:3072
	ds_read_b128 v[204:207], v189 offset:4096
	ds_read_b128 v[208:211], v189 offset:5120
	ds_read_b128 v[212:215], v189 offset:6144
	ds_read_b128 v[216:219], v189 offset:7168
	global_load_lds_dwordx4 v166, s[46:47]
	s_add_i32 m0, s13, 0xe000
	s_nop 0
	global_load_lds_dwordx4 v168, s[46:47]
	s_waitcnt vmcnt(8) lgkmcnt(0)
	s_barrier
	v_mfma_f32_16x16x32_bf16 v[126:129], v[130:133], v[184:187], v[126:129]
	v_mfma_f32_16x16x32_bf16 v[126:129], v[134:137], v[192:195], v[126:129]
	v_mfma_f32_16x16x32_bf16 v[122:125], v[138:141], v[184:187], v[122:125]
	v_mfma_f32_16x16x32_bf16 v[122:125], v[142:145], v[192:195], v[122:125]
	v_mfma_f32_16x16x32_bf16 v[118:121], v[146:149], v[184:187], v[118:121]
	v_mfma_f32_16x16x32_bf16 v[118:121], v[150:153], v[192:195], v[118:121]
	v_mfma_f32_16x16x32_bf16 v[114:117], v[174:177], v[184:187], v[114:117]
	v_mfma_f32_16x16x32_bf16 v[114:117], v[178:181], v[192:195], v[114:117]
	v_mfma_f32_16x16x32_bf16 v[110:113], v[130:133], v[196:199], v[110:113]
	v_mfma_f32_16x16x32_bf16 v[110:113], v[134:137], v[200:203], v[110:113]
	v_mfma_f32_16x16x32_bf16 v[106:109], v[138:141], v[196:199], v[106:109]
	v_mfma_f32_16x16x32_bf16 v[106:109], v[142:145], v[200:203], v[106:109]
	v_mfma_f32_16x16x32_bf16 v[102:105], v[146:149], v[196:199], v[102:105]
	v_mfma_f32_16x16x32_bf16 v[102:105], v[150:153], v[200:203], v[102:105]
	v_mfma_f32_16x16x32_bf16 v[98:101], v[174:177], v[196:199], v[98:101]
	v_mfma_f32_16x16x32_bf16 v[98:101], v[178:181], v[200:203], v[98:101]
	v_mfma_f32_16x16x32_bf16 v[94:97], v[130:133], v[204:207], v[94:97]
	v_mfma_f32_16x16x32_bf16 v[94:97], v[134:137], v[208:211], v[94:97]
	v_mfma_f32_16x16x32_bf16 v[90:93], v[138:141], v[204:207], v[90:93]
	v_mfma_f32_16x16x32_bf16 v[90:93], v[142:145], v[208:211], v[90:93]
	v_mfma_f32_16x16x32_bf16 v[86:89], v[146:149], v[204:207], v[86:89]
	v_mfma_f32_16x16x32_bf16 v[86:89], v[150:153], v[208:211], v[86:89]
	v_mfma_f32_16x16x32_bf16 v[82:85], v[174:177], v[204:207], v[82:85]
	v_mfma_f32_16x16x32_bf16 v[82:85], v[178:181], v[208:211], v[82:85]
	v_mfma_f32_16x16x32_bf16 v[78:81], v[130:133], v[212:215], v[78:81]
	v_mfma_f32_16x16x32_bf16 v[78:81], v[134:137], v[216:219], v[78:81]
	v_mfma_f32_16x16x32_bf16 v[74:77], v[138:141], v[212:215], v[74:77]
	v_mfma_f32_16x16x32_bf16 v[74:77], v[142:145], v[216:219], v[74:77]
	v_mfma_f32_16x16x32_bf16 v[70:73], v[146:149], v[212:215], v[70:73]
	v_mfma_f32_16x16x32_bf16 v[70:73], v[150:153], v[216:219], v[70:73]
	v_mfma_f32_16x16x32_bf16 v[66:69], v[174:177], v[212:215], v[66:69]
	v_mfma_f32_16x16x32_bf16 v[66:69], v[178:181], v[216:219], v[66:69]
	s_barrier
	s_add_i32 s74, s67, s3
	s_add_u32 s98, s48, 0x80
	s_addc_u32 s99, s49, 0
	s_mov_b32 m0, s74
	ds_read_b128 v[184:187], v189 offset:16384
	ds_read_b128 v[192:195], v189 offset:17408
	ds_read_b128 v[196:199], v189 offset:18432
	ds_read_b128 v[200:203], v189 offset:19456
	ds_read_b128 v[204:207], v189 offset:20480
	ds_read_b128 v[208:211], v189 offset:21504
	ds_read_b128 v[212:215], v189 offset:22528
	ds_read_b128 v[216:219], v189 offset:23552
	global_load_lds_dwordx4 v156, s[48:49]
	s_add_i32 m0, s74, 0x2000
	s_add_u32 s74, s48, 0x100000
	s_addc_u32 s75, s49, 0
	s_add_i32 s76, s68, s3
	global_load_lds_dwordx4 v160, s[48:49]
	s_mov_b32 m0, s76
	global_load_lds_dwordx4 v156, s[74:75]
	s_add_i32 m0, s76, 0x2000
	s_nop 0
	global_load_lds_dwordx4 v160, s[74:75]
	s_add_u32 s100, s50, 0x80
	s_addc_u32 s101, s51, 0
	s_mov_b32 m0, s13
	s_nop 0
	global_load_lds_dwordx4 v154, s[50:51]
	s_mov_b32 m0, s21
	s_nop 0
	global_load_lds_dwordx4 v158, s[50:51]
	s_waitcnt vmcnt(8) lgkmcnt(0)
	s_barrier
	v_mfma_f32_16x16x32_bf16 v[62:65], v[130:133], v[184:187], v[62:65]
	v_mfma_f32_16x16x32_bf16 v[62:65], v[134:137], v[192:195], v[62:65]
	v_mfma_f32_16x16x32_bf16 v[58:61], v[138:141], v[184:187], v[58:61]
	v_mfma_f32_16x16x32_bf16 v[58:61], v[142:145], v[192:195], v[58:61]
	v_mfma_f32_16x16x32_bf16 v[54:57], v[146:149], v[184:187], v[54:57]
	v_mfma_f32_16x16x32_bf16 v[54:57], v[150:153], v[192:195], v[54:57]
	v_mfma_f32_16x16x32_bf16 v[50:53], v[174:177], v[184:187], v[50:53]
	v_mfma_f32_16x16x32_bf16 v[50:53], v[178:181], v[192:195], v[50:53]
	v_mfma_f32_16x16x32_bf16 v[46:49], v[130:133], v[196:199], v[46:49]
	v_mfma_f32_16x16x32_bf16 v[46:49], v[134:137], v[200:203], v[46:49]
	v_mfma_f32_16x16x32_bf16 v[42:45], v[138:141], v[196:199], v[42:45]
	v_mfma_f32_16x16x32_bf16 v[42:45], v[142:145], v[200:203], v[42:45]
	v_mfma_f32_16x16x32_bf16 v[38:41], v[146:149], v[196:199], v[38:41]
	v_mfma_f32_16x16x32_bf16 v[38:41], v[150:153], v[200:203], v[38:41]
	v_mfma_f32_16x16x32_bf16 v[34:37], v[174:177], v[196:199], v[34:37]
	v_mfma_f32_16x16x32_bf16 v[34:37], v[178:181], v[200:203], v[34:37]
	v_mfma_f32_16x16x32_bf16 v[30:33], v[130:133], v[204:207], v[30:33]
	v_mfma_f32_16x16x32_bf16 v[30:33], v[134:137], v[208:211], v[30:33]
	v_mfma_f32_16x16x32_bf16 v[26:29], v[138:141], v[204:207], v[26:29]
	v_mfma_f32_16x16x32_bf16 v[26:29], v[142:145], v[208:211], v[26:29]
	v_mfma_f32_16x16x32_bf16 v[22:25], v[146:149], v[204:207], v[22:25]
	v_mfma_f32_16x16x32_bf16 v[22:25], v[150:153], v[208:211], v[22:25]
	v_mfma_f32_16x16x32_bf16 v[18:21], v[174:177], v[204:207], v[18:21]
	v_mfma_f32_16x16x32_bf16 v[18:21], v[178:181], v[208:211], v[18:21]
	v_mfma_f32_16x16x32_bf16 v[14:17], v[130:133], v[212:215], v[14:17]
	v_mfma_f32_16x16x32_bf16 v[14:17], v[134:137], v[216:219], v[14:17]
	v_mfma_f32_16x16x32_bf16 v[10:13], v[138:141], v[212:215], v[10:13]
	v_mfma_f32_16x16x32_bf16 v[10:13], v[142:145], v[216:219], v[10:13]
	v_mfma_f32_16x16x32_bf16 v[6:9], v[146:149], v[212:215], v[6:9]
	v_mfma_f32_16x16x32_bf16 v[6:9], v[150:153], v[216:219], v[6:9]
	v_mfma_f32_16x16x32_bf16 v[2:5], v[174:177], v[212:215], v[2:5]
	v_mfma_f32_16x16x32_bf16 v[2:5], v[178:181], v[216:219], v[2:5]
	s_barrier
	s_add_i32 s74, 0, 0x18000
	s_add_i32 s75, 0, 0x1c000
	ds_read_b128 v[130:133], v246
	ds_read_b128 v[134:137], v246 offset:1024
	ds_read_b128 v[138:141], v246 offset:2048
	ds_read_b128 v[142:145], v246 offset:3072
	ds_read_b128 v[146:149], v247
	ds_read_b128 v[150:153], v247 offset:1024
	ds_read_b128 v[174:177], v247 offset:2048
	ds_read_b128 v[178:181], v247 offset:3072
	s_add_u32 s50, s50, 0x100000
	s_addc_u32 s51, s51, 0
	s_mov_b32 m0, s33
	ds_read_b128 v[184:187], v189 offset:32768
	ds_read_b128 v[192:195], v189 offset:33792
	ds_read_b128 v[196:199], v189 offset:34816
	ds_read_b128 v[200:203], v189 offset:35840
	ds_read_b128 v[204:207], v189 offset:36864
	ds_read_b128 v[208:211], v189 offset:37888
	ds_read_b128 v[212:215], v189 offset:38912
	ds_read_b128 v[216:219], v189 offset:39936
	global_load_lds_dwordx4 v154, s[50:51]
	s_mov_b32 m0, s35
	s_nop 0
	global_load_lds_dwordx4 v158, s[50:51]
	s_waitcnt vmcnt(8) lgkmcnt(0)
	s_barrier
	v_mfma_f32_16x16x32_bf16 v[126:129], v[130:133], v[184:187], v[126:129]
	v_mfma_f32_16x16x32_bf16 v[126:129], v[134:137], v[192:195], v[126:129]
	v_mfma_f32_16x16x32_bf16 v[122:125], v[138:141], v[184:187], v[122:125]
	v_mfma_f32_16x16x32_bf16 v[122:125], v[142:145], v[192:195], v[122:125]
	v_mfma_f32_16x16x32_bf16 v[118:121], v[146:149], v[184:187], v[118:121]
	v_mfma_f32_16x16x32_bf16 v[118:121], v[150:153], v[192:195], v[118:121]
	v_mfma_f32_16x16x32_bf16 v[114:117], v[174:177], v[184:187], v[114:117]
	v_mfma_f32_16x16x32_bf16 v[114:117], v[178:181], v[192:195], v[114:117]
	v_mfma_f32_16x16x32_bf16 v[110:113], v[130:133], v[196:199], v[110:113]
	v_mfma_f32_16x16x32_bf16 v[110:113], v[134:137], v[200:203], v[110:113]
	v_mfma_f32_16x16x32_bf16 v[106:109], v[138:141], v[196:199], v[106:109]
	v_mfma_f32_16x16x32_bf16 v[106:109], v[142:145], v[200:203], v[106:109]
	v_mfma_f32_16x16x32_bf16 v[102:105], v[146:149], v[196:199], v[102:105]
	v_mfma_f32_16x16x32_bf16 v[102:105], v[150:153], v[200:203], v[102:105]
	v_mfma_f32_16x16x32_bf16 v[98:101], v[174:177], v[196:199], v[98:101]
	v_mfma_f32_16x16x32_bf16 v[98:101], v[178:181], v[200:203], v[98:101]
	v_mfma_f32_16x16x32_bf16 v[94:97], v[130:133], v[204:207], v[94:97]
	v_mfma_f32_16x16x32_bf16 v[94:97], v[134:137], v[208:211], v[94:97]
	v_mfma_f32_16x16x32_bf16 v[90:93], v[138:141], v[204:207], v[90:93]
	v_mfma_f32_16x16x32_bf16 v[90:93], v[142:145], v[208:211], v[90:93]
	v_mfma_f32_16x16x32_bf16 v[86:89], v[146:149], v[204:207], v[86:89]
	v_mfma_f32_16x16x32_bf16 v[86:89], v[150:153], v[208:211], v[86:89]
	v_mfma_f32_16x16x32_bf16 v[82:85], v[174:177], v[204:207], v[82:85]
	v_mfma_f32_16x16x32_bf16 v[82:85], v[178:181], v[208:211], v[82:85]
	v_mfma_f32_16x16x32_bf16 v[78:81], v[130:133], v[212:215], v[78:81]
	v_mfma_f32_16x16x32_bf16 v[78:81], v[134:137], v[216:219], v[78:81]
	v_mfma_f32_16x16x32_bf16 v[74:77], v[138:141], v[212:215], v[74:77]
	v_mfma_f32_16x16x32_bf16 v[74:77], v[142:145], v[216:219], v[74:77]
	v_mfma_f32_16x16x32_bf16 v[70:73], v[146:149], v[212:215], v[70:73]
	v_mfma_f32_16x16x32_bf16 v[70:73], v[150:153], v[216:219], v[70:73]
	v_mfma_f32_16x16x32_bf16 v[66:69], v[174:177], v[212:215], v[66:69]
	v_mfma_f32_16x16x32_bf16 v[66:69], v[178:181], v[216:219], v[66:69]
	s_barrier
	s_add_i32 s50, s74, s3
	s_mov_b32 m0, s50
	ds_read_b128 v[184:187], v189 offset:49152
	ds_read_b128 v[192:195], v189 offset:50176
	ds_read_b128 v[196:199], v189 offset:51200
	ds_read_b128 v[200:203], v189 offset:52224
	ds_read_b128 v[204:207], v189 offset:53248
	ds_read_b128 v[208:211], v189 offset:54272
	ds_read_b128 v[212:215], v189 offset:55296
	ds_read_b128 v[216:219], v189 offset:56320
	global_load_lds_dwordx4 v156, s[98:99]
	s_add_i32 m0, s50, 0x2000
	s_add_u32 s48, s48, 0x100080
	s_addc_u32 s49, s49, 0
	s_add_i32 s50, s75, s3
	global_load_lds_dwordx4 v160, s[98:99]
	s_mov_b32 m0, s50
	s_nop 0
	global_load_lds_dwordx4 v156, s[48:49]
	s_add_i32 m0, s50, 0x2000
	s_nop 0
	global_load_lds_dwordx4 v160, s[48:49]
	s_mov_b32 m0, s62
	s_nop 0
	global_load_lds_dwordx4 v154, s[100:101]
	s_mov_b32 m0, s63
	s_nop 0
	global_load_lds_dwordx4 v158, s[100:101]
	s_waitcnt vmcnt(8) lgkmcnt(0)
	s_barrier
	v_mfma_f32_16x16x32_bf16 v[62:65], v[130:133], v[184:187], v[62:65]
	v_mfma_f32_16x16x32_bf16 v[62:65], v[134:137], v[192:195], v[62:65]
	v_mfma_f32_16x16x32_bf16 v[58:61], v[138:141], v[184:187], v[58:61]
	v_mfma_f32_16x16x32_bf16 v[58:61], v[142:145], v[192:195], v[58:61]
	v_mfma_f32_16x16x32_bf16 v[54:57], v[146:149], v[184:187], v[54:57]
	v_mfma_f32_16x16x32_bf16 v[54:57], v[150:153], v[192:195], v[54:57]
	v_mfma_f32_16x16x32_bf16 v[50:53], v[174:177], v[184:187], v[50:53]
	v_mfma_f32_16x16x32_bf16 v[50:53], v[178:181], v[192:195], v[50:53]
	v_mfma_f32_16x16x32_bf16 v[46:49], v[130:133], v[196:199], v[46:49]
	v_mfma_f32_16x16x32_bf16 v[46:49], v[134:137], v[200:203], v[46:49]
	v_mfma_f32_16x16x32_bf16 v[42:45], v[138:141], v[196:199], v[42:45]
	v_mfma_f32_16x16x32_bf16 v[42:45], v[142:145], v[200:203], v[42:45]
	v_mfma_f32_16x16x32_bf16 v[38:41], v[146:149], v[196:199], v[38:41]
	v_mfma_f32_16x16x32_bf16 v[38:41], v[150:153], v[200:203], v[38:41]
	v_mfma_f32_16x16x32_bf16 v[34:37], v[174:177], v[196:199], v[34:37]
	v_mfma_f32_16x16x32_bf16 v[34:37], v[178:181], v[200:203], v[34:37]
	v_mfma_f32_16x16x32_bf16 v[30:33], v[130:133], v[204:207], v[30:33]
	v_mfma_f32_16x16x32_bf16 v[30:33], v[134:137], v[208:211], v[30:33]
	v_mfma_f32_16x16x32_bf16 v[26:29], v[138:141], v[204:207], v[26:29]
	v_mfma_f32_16x16x32_bf16 v[26:29], v[142:145], v[208:211], v[26:29]
	v_mfma_f32_16x16x32_bf16 v[22:25], v[146:149], v[204:207], v[22:25]
	v_mfma_f32_16x16x32_bf16 v[22:25], v[150:153], v[208:211], v[22:25]
	v_mfma_f32_16x16x32_bf16 v[18:21], v[174:177], v[204:207], v[18:21]
	v_mfma_f32_16x16x32_bf16 v[18:21], v[178:181], v[208:211], v[18:21]
	v_mfma_f32_16x16x32_bf16 v[14:17], v[130:133], v[212:215], v[14:17]
	v_mfma_f32_16x16x32_bf16 v[14:17], v[134:137], v[216:219], v[14:17]
	v_mfma_f32_16x16x32_bf16 v[10:13], v[138:141], v[212:215], v[10:13]
	v_mfma_f32_16x16x32_bf16 v[10:13], v[142:145], v[216:219], v[10:13]
	v_mfma_f32_16x16x32_bf16 v[6:9], v[146:149], v[212:215], v[6:9]
	v_mfma_f32_16x16x32_bf16 v[6:9], v[150:153], v[216:219], v[6:9]
	v_mfma_f32_16x16x32_bf16 v[2:5], v[174:177], v[212:215], v[2:5]
	v_mfma_f32_16x16x32_bf16 v[2:5], v[178:181], v[216:219], v[2:5]
	s_barrier
	s_add_i32 s73, s73, 2
	s_add_u32 s46, s46, 0x100
	s_addc_u32 s47, s47, 0
	s_add_u32 s71, s71, 0x100
	s_addc_u32 s72, s72, 0
	s_cmp_gt_u32 s73, 61
	s_cbranch_scc0 .LBB0_2635
	s_setprio 0
	s_and_b64 vcc, exec, s[36:37]
	s_cbranch_vccz .LBB0_2638
	s_barrier

.LBB0_2720:
	ds_read_b128 v[148:151], v159
	ds_read_b128 v[164:167], v159 offset:1024
	ds_read_b128 v[168:171], v159 offset:2048
	ds_read_b128 v[172:175], v159 offset:3072
	ds_read_b128 v[176:179], v160
	ds_read_b128 v[184:187], v160 offset:1024
	ds_read_b128 v[188:191], v160 offset:2048
	ds_read_b128 v[192:195], v160 offset:3072
	s_add_u32 s40, s6, 0xfff00080
	s_addc_u32 s41, s7, -1
	s_cmp_eq_u32 s82, 60
	s_cselect_b32 s43, s29, s41
	s_cselect_b32 s42, s78, s40
	s_cselect_b32 s41, s27, s81
	s_cselect_b32 s40, s79, s80
	s_add_i32 m0, s44, 0xc000
	ds_read_b128 v[196:199], v161
	ds_read_b128 v[200:203], v161 offset:1024
	ds_read_b128 v[204:207], v161 offset:2048
	ds_read_b128 v[208:211], v161 offset:3072
	ds_read_b128 v[212:215], v161 offset:4096
	ds_read_b128 v[216:219], v161 offset:5120
	ds_read_b128 v[220:223], v161 offset:6144
	ds_read_b128 v[224:227], v161 offset:7168
	global_load_lds_dwordx4 v140, s[6:7]
	s_add_i32 m0, s44, 0xe000
	s_nop 0
	global_load_lds_dwordx4 v142, s[6:7]
	s_waitcnt vmcnt(8) lgkmcnt(0)
	s_barrier
	v_mfma_f32_16x16x32_bf16 v[126:129], v[148:151], v[196:199], v[126:129]
	v_mfma_f32_16x16x32_bf16 v[126:129], v[164:167], v[200:203], v[126:129]
	v_mfma_f32_16x16x32_bf16 v[118:121], v[168:171], v[196:199], v[118:121]
	v_mfma_f32_16x16x32_bf16 v[118:121], v[172:175], v[200:203], v[118:121]
	v_mfma_f32_16x16x32_bf16 v[122:125], v[176:179], v[196:199], v[122:125]
	v_mfma_f32_16x16x32_bf16 v[122:125], v[184:187], v[200:203], v[122:125]
	v_mfma_f32_16x16x32_bf16 v[114:117], v[188:191], v[196:199], v[114:117]
	v_mfma_f32_16x16x32_bf16 v[114:117], v[192:195], v[200:203], v[114:117]
	v_mfma_f32_16x16x32_bf16 v[110:113], v[148:151], v[204:207], v[110:113]
	v_mfma_f32_16x16x32_bf16 v[110:113], v[164:167], v[208:211], v[110:113]
	v_mfma_f32_16x16x32_bf16 v[102:105], v[168:171], v[204:207], v[102:105]
	v_mfma_f32_16x16x32_bf16 v[102:105], v[172:175], v[208:211], v[102:105]
	v_mfma_f32_16x16x32_bf16 v[106:109], v[176:179], v[204:207], v[106:109]
	v_mfma_f32_16x16x32_bf16 v[106:109], v[184:187], v[208:211], v[106:109]
	v_mfma_f32_16x16x32_bf16 v[98:101], v[188:191], v[204:207], v[98:101]
	v_mfma_f32_16x16x32_bf16 v[98:101], v[192:195], v[208:211], v[98:101]
	v_mfma_f32_16x16x32_bf16 v[94:97], v[148:151], v[212:215], v[94:97]
	v_mfma_f32_16x16x32_bf16 v[94:97], v[164:167], v[216:219], v[94:97]
	v_mfma_f32_16x16x32_bf16 v[86:89], v[168:171], v[212:215], v[86:89]
	v_mfma_f32_16x16x32_bf16 v[86:89], v[172:175], v[216:219], v[86:89]
	v_mfma_f32_16x16x32_bf16 v[90:93], v[176:179], v[212:215], v[90:93]
	v_mfma_f32_16x16x32_bf16 v[90:93], v[184:187], v[216:219], v[90:93]
	v_mfma_f32_16x16x32_bf16 v[82:85], v[188:191], v[212:215], v[82:85]
	v_mfma_f32_16x16x32_bf16 v[82:85], v[192:195], v[216:219], v[82:85]
	v_mfma_f32_16x16x32_bf16 v[78:81], v[148:151], v[220:223], v[78:81]
	v_mfma_f32_16x16x32_bf16 v[78:81], v[164:167], v[224:227], v[78:81]
	v_mfma_f32_16x16x32_bf16 v[70:73], v[168:171], v[220:223], v[70:73]
	v_mfma_f32_16x16x32_bf16 v[70:73], v[172:175], v[224:227], v[70:73]
	v_mfma_f32_16x16x32_bf16 v[74:77], v[176:179], v[220:223], v[74:77]
	v_mfma_f32_16x16x32_bf16 v[74:77], v[184:187], v[224:227], v[74:77]
	v_mfma_f32_16x16x32_bf16 v[66:69], v[188:191], v[220:223], v[66:69]
	v_mfma_f32_16x16x32_bf16 v[66:69], v[192:195], v[224:227], v[66:69]
	s_barrier
	s_add_i32 s83, s68, s13
	s_add_u32 s98, s40, 0x80
	s_addc_u32 s99, s41, 0
	s_mov_b32 m0, s83
	ds_read_b128 v[196:199], v161 offset:16384
	ds_read_b128 v[200:203], v161 offset:17408
	ds_read_b128 v[204:207], v161 offset:18432
	ds_read_b128 v[208:211], v161 offset:19456
	ds_read_b128 v[212:215], v161 offset:20480
	ds_read_b128 v[216:219], v161 offset:21504
	ds_read_b128 v[220:223], v161 offset:22528
	ds_read_b128 v[224:227], v161 offset:23552
	global_load_lds_dwordx4 v132, s[40:41]
	s_add_i32 m0, s83, 0x2000
	s_add_u32 s84, s40, 0x100000
	s_addc_u32 s85, s41, 0
	s_add_i32 s83, s69, s13
	global_load_lds_dwordx4 v136, s[40:41]
	s_mov_b32 m0, s83
	global_load_lds_dwordx4 v132, s[84:85]
	s_add_i32 m0, s83, 0x2000
	s_nop 0
	global_load_lds_dwordx4 v136, s[84:85]
	s_add_u32 s100, s42, 0x80
	s_addc_u32 s101, s43, 0
	s_mov_b32 m0, s44
	s_nop 0
	global_load_lds_dwordx4 v130, s[42:43]
	s_mov_b32 m0, s45
	s_nop 0
	global_load_lds_dwordx4 v134, s[42:43]
	s_waitcnt vmcnt(8) lgkmcnt(0)
	s_barrier
	v_mfma_f32_16x16x32_bf16 v[62:65], v[148:151], v[196:199], v[62:65]
	v_mfma_f32_16x16x32_bf16 v[62:65], v[164:167], v[200:203], v[62:65]
	v_mfma_f32_16x16x32_bf16 v[54:57], v[168:171], v[196:199], v[54:57]
	v_mfma_f32_16x16x32_bf16 v[54:57], v[172:175], v[200:203], v[54:57]
	v_mfma_f32_16x16x32_bf16 v[58:61], v[176:179], v[196:199], v[58:61]
	v_mfma_f32_16x16x32_bf16 v[58:61], v[184:187], v[200:203], v[58:61]
	v_mfma_f32_16x16x32_bf16 v[50:53], v[188:191], v[196:199], v[50:53]
	v_mfma_f32_16x16x32_bf16 v[50:53], v[192:195], v[200:203], v[50:53]
	v_mfma_f32_16x16x32_bf16 v[46:49], v[148:151], v[204:207], v[46:49]
	v_mfma_f32_16x16x32_bf16 v[46:49], v[164:167], v[208:211], v[46:49]
	v_mfma_f32_16x16x32_bf16 v[38:41], v[168:171], v[204:207], v[38:41]
	v_mfma_f32_16x16x32_bf16 v[38:41], v[172:175], v[208:211], v[38:41]
	v_mfma_f32_16x16x32_bf16 v[42:45], v[176:179], v[204:207], v[42:45]
	v_mfma_f32_16x16x32_bf16 v[42:45], v[184:187], v[208:211], v[42:45]
	v_mfma_f32_16x16x32_bf16 v[34:37], v[188:191], v[204:207], v[34:37]
	v_mfma_f32_16x16x32_bf16 v[34:37], v[192:195], v[208:211], v[34:37]
	v_mfma_f32_16x16x32_bf16 v[30:33], v[148:151], v[212:215], v[30:33]
	v_mfma_f32_16x16x32_bf16 v[30:33], v[164:167], v[216:219], v[30:33]
	v_mfma_f32_16x16x32_bf16 v[22:25], v[168:171], v[212:215], v[22:25]
	v_mfma_f32_16x16x32_bf16 v[22:25], v[172:175], v[216:219], v[22:25]
	v_mfma_f32_16x16x32_bf16 v[26:29], v[176:179], v[212:215], v[26:29]
	v_mfma_f32_16x16x32_bf16 v[26:29], v[184:187], v[216:219], v[26:29]
	v_mfma_f32_16x16x32_bf16 v[18:21], v[188:191], v[212:215], v[18:21]
	v_mfma_f32_16x16x32_bf16 v[18:21], v[192:195], v[216:219], v[18:21]
	v_mfma_f32_16x16x32_bf16 v[14:17], v[148:151], v[220:223], v[14:17]
	v_mfma_f32_16x16x32_bf16 v[14:17], v[164:167], v[224:227], v[14:17]
	v_mfma_f32_16x16x32_bf16 v[6:9], v[168:171], v[220:223], v[6:9]
	v_mfma_f32_16x16x32_bf16 v[6:9], v[172:175], v[224:227], v[6:9]
	v_mfma_f32_16x16x32_bf16 v[10:13], v[176:179], v[220:223], v[10:13]
	v_mfma_f32_16x16x32_bf16 v[10:13], v[184:187], v[224:227], v[10:13]
	v_mfma_f32_16x16x32_bf16 v[2:5], v[188:191], v[220:223], v[2:5]
	v_mfma_f32_16x16x32_bf16 v[2:5], v[192:195], v[224:227], v[2:5]
	s_barrier
	s_add_i32 s83, 0, 0x18000
	s_add_i32 s84, 0, 0x1c000
	ds_read_b128 v[148:151], v246
	ds_read_b128 v[164:167], v246 offset:1024
	ds_read_b128 v[168:171], v246 offset:2048
	ds_read_b128 v[172:175], v246 offset:3072
	ds_read_b128 v[176:179], v247
	ds_read_b128 v[184:187], v247 offset:1024
	ds_read_b128 v[188:191], v247 offset:2048
	ds_read_b128 v[192:195], v247 offset:3072
	s_add_u32 s42, s42, 0x100000
	s_addc_u32 s43, s43, 0
	s_mov_b32 m0, s46
	ds_read_b128 v[196:199], v161 offset:32768
	ds_read_b128 v[200:203], v161 offset:33792
	ds_read_b128 v[204:207], v161 offset:34816
	ds_read_b128 v[208:211], v161 offset:35840
	ds_read_b128 v[212:215], v161 offset:36864
	ds_read_b128 v[216:219], v161 offset:37888
	ds_read_b128 v[220:223], v161 offset:38912
	ds_read_b128 v[224:227], v161 offset:39936
	global_load_lds_dwordx4 v130, s[42:43]
	s_mov_b32 m0, s47
	s_nop 0
	global_load_lds_dwordx4 v134, s[42:43]
	s_waitcnt vmcnt(8) lgkmcnt(0)
	s_barrier
	v_mfma_f32_16x16x32_bf16 v[126:129], v[148:151], v[196:199], v[126:129]
	v_mfma_f32_16x16x32_bf16 v[126:129], v[164:167], v[200:203], v[126:129]
	v_mfma_f32_16x16x32_bf16 v[118:121], v[168:171], v[196:199], v[118:121]
	v_mfma_f32_16x16x32_bf16 v[118:121], v[172:175], v[200:203], v[118:121]
	v_mfma_f32_16x16x32_bf16 v[122:125], v[176:179], v[196:199], v[122:125]
	v_mfma_f32_16x16x32_bf16 v[122:125], v[184:187], v[200:203], v[122:125]
	v_mfma_f32_16x16x32_bf16 v[114:117], v[188:191], v[196:199], v[114:117]
	v_mfma_f32_16x16x32_bf16 v[114:117], v[192:195], v[200:203], v[114:117]
	v_mfma_f32_16x16x32_bf16 v[110:113], v[148:151], v[204:207], v[110:113]
	v_mfma_f32_16x16x32_bf16 v[110:113], v[164:167], v[208:211], v[110:113]
	v_mfma_f32_16x16x32_bf16 v[102:105], v[168:171], v[204:207], v[102:105]
	v_mfma_f32_16x16x32_bf16 v[102:105], v[172:175], v[208:211], v[102:105]
	v_mfma_f32_16x16x32_bf16 v[106:109], v[176:179], v[204:207], v[106:109]
	v_mfma_f32_16x16x32_bf16 v[106:109], v[184:187], v[208:211], v[106:109]
	v_mfma_f32_16x16x32_bf16 v[98:101], v[188:191], v[204:207], v[98:101]
	v_mfma_f32_16x16x32_bf16 v[98:101], v[192:195], v[208:211], v[98:101]
	v_mfma_f32_16x16x32_bf16 v[94:97], v[148:151], v[212:215], v[94:97]
	v_mfma_f32_16x16x32_bf16 v[94:97], v[164:167], v[216:219], v[94:97]
	v_mfma_f32_16x16x32_bf16 v[86:89], v[168:171], v[212:215], v[86:89]
	v_mfma_f32_16x16x32_bf16 v[86:89], v[172:175], v[216:219], v[86:89]
	v_mfma_f32_16x16x32_bf16 v[90:93], v[176:179], v[212:215], v[90:93]
	v_mfma_f32_16x16x32_bf16 v[90:93], v[184:187], v[216:219], v[90:93]
	v_mfma_f32_16x16x32_bf16 v[82:85], v[188:191], v[212:215], v[82:85]
	v_mfma_f32_16x16x32_bf16 v[82:85], v[192:195], v[216:219], v[82:85]
	v_mfma_f32_16x16x32_bf16 v[78:81], v[148:151], v[220:223], v[78:81]
	v_mfma_f32_16x16x32_bf16 v[78:81], v[164:167], v[224:227], v[78:81]
	v_mfma_f32_16x16x32_bf16 v[70:73], v[168:171], v[220:223], v[70:73]
	v_mfma_f32_16x16x32_bf16 v[70:73], v[172:175], v[224:227], v[70:73]
	v_mfma_f32_16x16x32_bf16 v[74:77], v[176:179], v[220:223], v[74:77]
	v_mfma_f32_16x16x32_bf16 v[74:77], v[184:187], v[224:227], v[74:77]
	v_mfma_f32_16x16x32_bf16 v[66:69], v[188:191], v[220:223], v[66:69]
	v_mfma_f32_16x16x32_bf16 v[66:69], v[192:195], v[224:227], v[66:69]
	s_barrier
	s_add_i32 s42, s83, s13
	s_mov_b32 m0, s42
	ds_read_b128 v[196:199], v161 offset:49152
	ds_read_b128 v[200:203], v161 offset:50176
	ds_read_b128 v[204:207], v161 offset:51200
	ds_read_b128 v[208:211], v161 offset:52224
	ds_read_b128 v[212:215], v161 offset:53248
	ds_read_b128 v[216:219], v161 offset:54272
	ds_read_b128 v[220:223], v161 offset:55296
	ds_read_b128 v[224:227], v161 offset:56320
	global_load_lds_dwordx4 v132, s[98:99]
	s_add_i32 m0, s42, 0x2000
	s_add_u32 s40, s40, 0x100080
	s_addc_u32 s41, s41, 0
	s_add_i32 s42, s84, s13
	global_load_lds_dwordx4 v136, s[98:99]
	s_mov_b32 m0, s42
	s_nop 0
	global_load_lds_dwordx4 v132, s[40:41]
	s_add_i32 m0, s42, 0x2000
	s_nop 0
	global_load_lds_dwordx4 v136, s[40:41]
	s_mov_b32 m0, s59
	s_nop 0
	global_load_lds_dwordx4 v130, s[100:101]
	s_mov_b32 m0, s62
	s_nop 0
	global_load_lds_dwordx4 v134, s[100:101]
	s_waitcnt vmcnt(8) lgkmcnt(0)
	s_barrier
	v_mfma_f32_16x16x32_bf16 v[62:65], v[148:151], v[196:199], v[62:65]
	v_mfma_f32_16x16x32_bf16 v[62:65], v[164:167], v[200:203], v[62:65]
	v_mfma_f32_16x16x32_bf16 v[54:57], v[168:171], v[196:199], v[54:57]
	v_mfma_f32_16x16x32_bf16 v[54:57], v[172:175], v[200:203], v[54:57]
	v_mfma_f32_16x16x32_bf16 v[58:61], v[176:179], v[196:199], v[58:61]
	v_mfma_f32_16x16x32_bf16 v[58:61], v[184:187], v[200:203], v[58:61]
	v_mfma_f32_16x16x32_bf16 v[50:53], v[188:191], v[196:199], v[50:53]
	v_mfma_f32_16x16x32_bf16 v[50:53], v[192:195], v[200:203], v[50:53]
	v_mfma_f32_16x16x32_bf16 v[46:49], v[148:151], v[204:207], v[46:49]
	v_mfma_f32_16x16x32_bf16 v[46:49], v[164:167], v[208:211], v[46:49]
	v_mfma_f32_16x16x32_bf16 v[38:41], v[168:171], v[204:207], v[38:41]
	v_mfma_f32_16x16x32_bf16 v[38:41], v[172:175], v[208:211], v[38:41]
	v_mfma_f32_16x16x32_bf16 v[42:45], v[176:179], v[204:207], v[42:45]
	v_mfma_f32_16x16x32_bf16 v[42:45], v[184:187], v[208:211], v[42:45]
	v_mfma_f32_16x16x32_bf16 v[34:37], v[188:191], v[204:207], v[34:37]
	v_mfma_f32_16x16x32_bf16 v[34:37], v[192:195], v[208:211], v[34:37]
	v_mfma_f32_16x16x32_bf16 v[30:33], v[148:151], v[212:215], v[30:33]
	v_mfma_f32_16x16x32_bf16 v[30:33], v[164:167], v[216:219], v[30:33]
	v_mfma_f32_16x16x32_bf16 v[22:25], v[168:171], v[212:215], v[22:25]
	v_mfma_f32_16x16x32_bf16 v[22:25], v[172:175], v[216:219], v[22:25]
	v_mfma_f32_16x16x32_bf16 v[26:29], v[176:179], v[212:215], v[26:29]
	v_mfma_f32_16x16x32_bf16 v[26:29], v[184:187], v[216:219], v[26:29]
	v_mfma_f32_16x16x32_bf16 v[18:21], v[188:191], v[212:215], v[18:21]
	v_mfma_f32_16x16x32_bf16 v[18:21], v[192:195], v[216:219], v[18:21]
	v_mfma_f32_16x16x32_bf16 v[14:17], v[148:151], v[220:223], v[14:17]
	v_mfma_f32_16x16x32_bf16 v[14:17], v[164:167], v[224:227], v[14:17]
	v_mfma_f32_16x16x32_bf16 v[6:9], v[168:171], v[220:223], v[6:9]
	v_mfma_f32_16x16x32_bf16 v[6:9], v[172:175], v[224:227], v[6:9]
	v_mfma_f32_16x16x32_bf16 v[10:13], v[176:179], v[220:223], v[10:13]
	v_mfma_f32_16x16x32_bf16 v[10:13], v[184:187], v[224:227], v[10:13]
	v_mfma_f32_16x16x32_bf16 v[2:5], v[188:191], v[220:223], v[2:5]
	v_mfma_f32_16x16x32_bf16 v[2:5], v[192:195], v[224:227], v[2:5]
	s_barrier
	s_add_i32 s82, s82, 2
	s_add_u32 s6, s6, 0x100
	s_addc_u32 s7, s7, 0
	s_add_u32 s80, s80, 0x100
	s_addc_u32 s81, s81, 0
	s_cmp_gt_u32 s82, 61
	s_cbranch_scc0 .LBB0_2720
	s_setprio 0
	s_and_b64 vcc, exec, s[24:25]
	s_cbranch_vccz .LBB0_2723
	s_barrier

.LBB0_2805:
	ds_read_b128 v[130:133], v163
	ds_read_b128 v[134:137], v163 offset:1024
	ds_read_b128 v[138:141], v163 offset:2048
	ds_read_b128 v[142:145], v163 offset:3072
	ds_read_b128 v[146:149], v188
	ds_read_b128 v[150:153], v188 offset:1024
	ds_read_b128 v[174:177], v188 offset:2048
	ds_read_b128 v[178:181], v188 offset:3072
	s_add_u32 s28, s26, 0xffd50080
	s_addc_u32 s29, s27, -1
	s_cmpk_eq_i32 s62, 0xa8
	s_cselect_b32 s37, s7, s29
	s_cselect_b32 s36, s6, s28
	s_cselect_b32 s29, s25, s59
	s_cselect_b32 s28, s24, s12
	s_add_i32 m0, s38, 0xc000
	ds_read_b128 v[184:187], v189
	ds_read_b128 v[192:195], v189 offset:1024
	ds_read_b128 v[196:199], v189 offset:2048
	ds_read_b128 v[200:203], v189 offset:3072
	ds_read_b128 v[204:207], v189 offset:4096
	ds_read_b128 v[208:211], v189 offset:5120
	ds_read_b128 v[212:215], v189 offset:6144
	ds_read_b128 v[216:219], v189 offset:7168
	global_load_lds_dwordx4 v166, s[26:27]
	s_add_i32 m0, s38, 0xe000
	s_nop 0
	global_load_lds_dwordx4 v168, s[26:27]
	s_waitcnt vmcnt(8) lgkmcnt(0)
	s_barrier
	v_mfma_f32_16x16x32_bf16 v[126:129], v[130:133], v[184:187], v[126:129]
	v_mfma_f32_16x16x32_bf16 v[126:129], v[134:137], v[192:195], v[126:129]
	v_mfma_f32_16x16x32_bf16 v[122:125], v[138:141], v[184:187], v[122:125]
	v_mfma_f32_16x16x32_bf16 v[122:125], v[142:145], v[192:195], v[122:125]
	v_mfma_f32_16x16x32_bf16 v[118:121], v[146:149], v[184:187], v[118:121]
	v_mfma_f32_16x16x32_bf16 v[118:121], v[150:153], v[192:195], v[118:121]
	v_mfma_f32_16x16x32_bf16 v[114:117], v[174:177], v[184:187], v[114:117]
	v_mfma_f32_16x16x32_bf16 v[114:117], v[178:181], v[192:195], v[114:117]
	v_mfma_f32_16x16x32_bf16 v[110:113], v[130:133], v[196:199], v[110:113]
	v_mfma_f32_16x16x32_bf16 v[110:113], v[134:137], v[200:203], v[110:113]
	v_mfma_f32_16x16x32_bf16 v[106:109], v[138:141], v[196:199], v[106:109]
	v_mfma_f32_16x16x32_bf16 v[106:109], v[142:145], v[200:203], v[106:109]
	v_mfma_f32_16x16x32_bf16 v[102:105], v[146:149], v[196:199], v[102:105]
	v_mfma_f32_16x16x32_bf16 v[102:105], v[150:153], v[200:203], v[102:105]
	v_mfma_f32_16x16x32_bf16 v[98:101], v[174:177], v[196:199], v[98:101]
	v_mfma_f32_16x16x32_bf16 v[98:101], v[178:181], v[200:203], v[98:101]
	v_mfma_f32_16x16x32_bf16 v[94:97], v[130:133], v[204:207], v[94:97]
	v_mfma_f32_16x16x32_bf16 v[94:97], v[134:137], v[208:211], v[94:97]
	v_mfma_f32_16x16x32_bf16 v[90:93], v[138:141], v[204:207], v[90:93]
	v_mfma_f32_16x16x32_bf16 v[90:93], v[142:145], v[208:211], v[90:93]
	v_mfma_f32_16x16x32_bf16 v[86:89], v[146:149], v[204:207], v[86:89]
	v_mfma_f32_16x16x32_bf16 v[86:89], v[150:153], v[208:211], v[86:89]
	v_mfma_f32_16x16x32_bf16 v[82:85], v[174:177], v[204:207], v[82:85]
	v_mfma_f32_16x16x32_bf16 v[82:85], v[178:181], v[208:211], v[82:85]
	v_mfma_f32_16x16x32_bf16 v[78:81], v[130:133], v[212:215], v[78:81]
	v_mfma_f32_16x16x32_bf16 v[78:81], v[134:137], v[216:219], v[78:81]
	v_mfma_f32_16x16x32_bf16 v[74:77], v[138:141], v[212:215], v[74:77]
	v_mfma_f32_16x16x32_bf16 v[74:77], v[142:145], v[216:219], v[74:77]
	v_mfma_f32_16x16x32_bf16 v[70:73], v[146:149], v[212:215], v[70:73]
	v_mfma_f32_16x16x32_bf16 v[70:73], v[150:153], v[216:219], v[70:73]
	v_mfma_f32_16x16x32_bf16 v[66:69], v[174:177], v[212:215], v[66:69]
	v_mfma_f32_16x16x32_bf16 v[66:69], v[178:181], v[216:219], v[66:69]
	s_barrier
	s_add_i32 s63, s47, s35
	s_add_u32 s98, s28, 0x80
	s_addc_u32 s99, s29, 0
	s_mov_b32 m0, s63
	ds_read_b128 v[184:187], v189 offset:16384
	ds_read_b128 v[192:195], v189 offset:17408
	ds_read_b128 v[196:199], v189 offset:18432
	ds_read_b128 v[200:203], v189 offset:19456
	ds_read_b128 v[204:207], v189 offset:20480
	ds_read_b128 v[208:211], v189 offset:21504
	ds_read_b128 v[212:215], v189 offset:22528
	ds_read_b128 v[216:219], v189 offset:23552
	global_load_lds_dwordx4 v156, s[28:29]
	s_add_i32 m0, s63, 0x2000
	s_add_u32 s66, s28, 0x2b0000
	s_addc_u32 s67, s29, 0
	s_add_i32 s63, s48, s35
	global_load_lds_dwordx4 v160, s[28:29]
	s_mov_b32 m0, s63
	global_load_lds_dwordx4 v156, s[66:67]
	s_add_i32 m0, s63, 0x2000
	s_nop 0
	global_load_lds_dwordx4 v160, s[66:67]
	s_add_u32 s100, s36, 0x80
	s_addc_u32 s101, s37, 0
	s_mov_b32 m0, s38
	s_nop 0
	global_load_lds_dwordx4 v154, s[36:37]
	s_mov_b32 m0, s39
	s_nop 0
	global_load_lds_dwordx4 v158, s[36:37]
	s_waitcnt vmcnt(8) lgkmcnt(0)
	s_barrier
	v_mfma_f32_16x16x32_bf16 v[62:65], v[130:133], v[184:187], v[62:65]
	v_mfma_f32_16x16x32_bf16 v[62:65], v[134:137], v[192:195], v[62:65]
	v_mfma_f32_16x16x32_bf16 v[58:61], v[138:141], v[184:187], v[58:61]
	v_mfma_f32_16x16x32_bf16 v[58:61], v[142:145], v[192:195], v[58:61]
	v_mfma_f32_16x16x32_bf16 v[54:57], v[146:149], v[184:187], v[54:57]
	v_mfma_f32_16x16x32_bf16 v[54:57], v[150:153], v[192:195], v[54:57]
	v_mfma_f32_16x16x32_bf16 v[50:53], v[174:177], v[184:187], v[50:53]
	v_mfma_f32_16x16x32_bf16 v[50:53], v[178:181], v[192:195], v[50:53]
	v_mfma_f32_16x16x32_bf16 v[46:49], v[130:133], v[196:199], v[46:49]
	v_mfma_f32_16x16x32_bf16 v[46:49], v[134:137], v[200:203], v[46:49]
	v_mfma_f32_16x16x32_bf16 v[42:45], v[138:141], v[196:199], v[42:45]
	v_mfma_f32_16x16x32_bf16 v[42:45], v[142:145], v[200:203], v[42:45]
	v_mfma_f32_16x16x32_bf16 v[38:41], v[146:149], v[196:199], v[38:41]
	v_mfma_f32_16x16x32_bf16 v[38:41], v[150:153], v[200:203], v[38:41]
	v_mfma_f32_16x16x32_bf16 v[34:37], v[174:177], v[196:199], v[34:37]
	v_mfma_f32_16x16x32_bf16 v[34:37], v[178:181], v[200:203], v[34:37]
	v_mfma_f32_16x16x32_bf16 v[30:33], v[130:133], v[204:207], v[30:33]
	v_mfma_f32_16x16x32_bf16 v[30:33], v[134:137], v[208:211], v[30:33]
	v_mfma_f32_16x16x32_bf16 v[26:29], v[138:141], v[204:207], v[26:29]
	v_mfma_f32_16x16x32_bf16 v[26:29], v[142:145], v[208:211], v[26:29]
	v_mfma_f32_16x16x32_bf16 v[22:25], v[146:149], v[204:207], v[22:25]
	v_mfma_f32_16x16x32_bf16 v[22:25], v[150:153], v[208:211], v[22:25]
	v_mfma_f32_16x16x32_bf16 v[18:21], v[174:177], v[204:207], v[18:21]
	v_mfma_f32_16x16x32_bf16 v[18:21], v[178:181], v[208:211], v[18:21]
	v_mfma_f32_16x16x32_bf16 v[14:17], v[130:133], v[212:215], v[14:17]
	v_mfma_f32_16x16x32_bf16 v[14:17], v[134:137], v[216:219], v[14:17]
	v_mfma_f32_16x16x32_bf16 v[10:13], v[138:141], v[212:215], v[10:13]
	v_mfma_f32_16x16x32_bf16 v[10:13], v[142:145], v[216:219], v[10:13]
	v_mfma_f32_16x16x32_bf16 v[6:9], v[146:149], v[212:215], v[6:9]
	v_mfma_f32_16x16x32_bf16 v[6:9], v[150:153], v[216:219], v[6:9]
	v_mfma_f32_16x16x32_bf16 v[2:5], v[174:177], v[212:215], v[2:5]
	v_mfma_f32_16x16x32_bf16 v[2:5], v[178:181], v[216:219], v[2:5]
	s_barrier
	s_add_i32 s63, 0, 0x18000
	s_add_i32 s65, 0, 0x1c000
	ds_read_b128 v[130:133], v246
	ds_read_b128 v[134:137], v246 offset:1024
	ds_read_b128 v[138:141], v246 offset:2048
	ds_read_b128 v[142:145], v246 offset:3072
	ds_read_b128 v[146:149], v247
	ds_read_b128 v[150:153], v247 offset:1024
	ds_read_b128 v[174:177], v247 offset:2048
	ds_read_b128 v[178:181], v247 offset:3072
	s_add_u32 s36, s36, 0x2b0000
	s_addc_u32 s37, s37, 0
	s_mov_b32 m0, s40
	ds_read_b128 v[184:187], v189 offset:32768
	ds_read_b128 v[192:195], v189 offset:33792
	ds_read_b128 v[196:199], v189 offset:34816
	ds_read_b128 v[200:203], v189 offset:35840
	ds_read_b128 v[204:207], v189 offset:36864
	ds_read_b128 v[208:211], v189 offset:37888
	ds_read_b128 v[212:215], v189 offset:38912
	ds_read_b128 v[216:219], v189 offset:39936
	global_load_lds_dwordx4 v154, s[36:37]
	s_mov_b32 m0, s41
	s_nop 0
	global_load_lds_dwordx4 v158, s[36:37]
	s_waitcnt vmcnt(8) lgkmcnt(0)
	s_barrier
	v_mfma_f32_16x16x32_bf16 v[126:129], v[130:133], v[184:187], v[126:129]
	v_mfma_f32_16x16x32_bf16 v[126:129], v[134:137], v[192:195], v[126:129]
	v_mfma_f32_16x16x32_bf16 v[122:125], v[138:141], v[184:187], v[122:125]
	v_mfma_f32_16x16x32_bf16 v[122:125], v[142:145], v[192:195], v[122:125]
	v_mfma_f32_16x16x32_bf16 v[118:121], v[146:149], v[184:187], v[118:121]
	v_mfma_f32_16x16x32_bf16 v[118:121], v[150:153], v[192:195], v[118:121]
	v_mfma_f32_16x16x32_bf16 v[114:117], v[174:177], v[184:187], v[114:117]
	v_mfma_f32_16x16x32_bf16 v[114:117], v[178:181], v[192:195], v[114:117]
	v_mfma_f32_16x16x32_bf16 v[110:113], v[130:133], v[196:199], v[110:113]
	v_mfma_f32_16x16x32_bf16 v[110:113], v[134:137], v[200:203], v[110:113]
	v_mfma_f32_16x16x32_bf16 v[106:109], v[138:141], v[196:199], v[106:109]
	v_mfma_f32_16x16x32_bf16 v[106:109], v[142:145], v[200:203], v[106:109]
	v_mfma_f32_16x16x32_bf16 v[102:105], v[146:149], v[196:199], v[102:105]
	v_mfma_f32_16x16x32_bf16 v[102:105], v[150:153], v[200:203], v[102:105]
	v_mfma_f32_16x16x32_bf16 v[98:101], v[174:177], v[196:199], v[98:101]
	v_mfma_f32_16x16x32_bf16 v[98:101], v[178:181], v[200:203], v[98:101]
	v_mfma_f32_16x16x32_bf16 v[94:97], v[130:133], v[204:207], v[94:97]
	v_mfma_f32_16x16x32_bf16 v[94:97], v[134:137], v[208:211], v[94:97]
	v_mfma_f32_16x16x32_bf16 v[90:93], v[138:141], v[204:207], v[90:93]
	v_mfma_f32_16x16x32_bf16 v[90:93], v[142:145], v[208:211], v[90:93]
	v_mfma_f32_16x16x32_bf16 v[86:89], v[146:149], v[204:207], v[86:89]
	v_mfma_f32_16x16x32_bf16 v[86:89], v[150:153], v[208:211], v[86:89]
	v_mfma_f32_16x16x32_bf16 v[82:85], v[174:177], v[204:207], v[82:85]
	v_mfma_f32_16x16x32_bf16 v[82:85], v[178:181], v[208:211], v[82:85]
	v_mfma_f32_16x16x32_bf16 v[78:81], v[130:133], v[212:215], v[78:81]
	v_mfma_f32_16x16x32_bf16 v[78:81], v[134:137], v[216:219], v[78:81]
	v_mfma_f32_16x16x32_bf16 v[74:77], v[138:141], v[212:215], v[74:77]
	v_mfma_f32_16x16x32_bf16 v[74:77], v[142:145], v[216:219], v[74:77]
	v_mfma_f32_16x16x32_bf16 v[70:73], v[146:149], v[212:215], v[70:73]
	v_mfma_f32_16x16x32_bf16 v[70:73], v[150:153], v[216:219], v[70:73]
	v_mfma_f32_16x16x32_bf16 v[66:69], v[174:177], v[212:215], v[66:69]
	v_mfma_f32_16x16x32_bf16 v[66:69], v[178:181], v[216:219], v[66:69]
	s_barrier
	s_add_i32 s36, s63, s35
	s_mov_b32 m0, s36
	ds_read_b128 v[184:187], v189 offset:49152
	ds_read_b128 v[192:195], v189 offset:50176
	ds_read_b128 v[196:199], v189 offset:51200
	ds_read_b128 v[200:203], v189 offset:52224
	ds_read_b128 v[204:207], v189 offset:53248
	ds_read_b128 v[208:211], v189 offset:54272
	ds_read_b128 v[212:215], v189 offset:55296
	ds_read_b128 v[216:219], v189 offset:56320
	global_load_lds_dwordx4 v156, s[98:99]
	s_add_i32 m0, s36, 0x2000
	s_add_u32 s28, s28, 0x2b0080
	s_addc_u32 s29, s29, 0
	s_add_i32 s36, s65, s35
	global_load_lds_dwordx4 v160, s[98:99]
	s_mov_b32 m0, s36
	s_nop 0
	global_load_lds_dwordx4 v156, s[28:29]
	s_add_i32 m0, s36, 0x2000
	s_nop 0
	global_load_lds_dwordx4 v160, s[28:29]
	s_mov_b32 m0, s43
	s_nop 0
	global_load_lds_dwordx4 v154, s[100:101]
	s_mov_b32 m0, s44
	s_nop 0
	global_load_lds_dwordx4 v158, s[100:101]
	s_waitcnt vmcnt(8) lgkmcnt(0)
	s_barrier
	v_mfma_f32_16x16x32_bf16 v[62:65], v[130:133], v[184:187], v[62:65]
	v_mfma_f32_16x16x32_bf16 v[62:65], v[134:137], v[192:195], v[62:65]
	v_mfma_f32_16x16x32_bf16 v[58:61], v[138:141], v[184:187], v[58:61]
	v_mfma_f32_16x16x32_bf16 v[58:61], v[142:145], v[192:195], v[58:61]
	v_mfma_f32_16x16x32_bf16 v[54:57], v[146:149], v[184:187], v[54:57]
	v_mfma_f32_16x16x32_bf16 v[54:57], v[150:153], v[192:195], v[54:57]
	v_mfma_f32_16x16x32_bf16 v[50:53], v[174:177], v[184:187], v[50:53]
	v_mfma_f32_16x16x32_bf16 v[50:53], v[178:181], v[192:195], v[50:53]
	v_mfma_f32_16x16x32_bf16 v[46:49], v[130:133], v[196:199], v[46:49]
	v_mfma_f32_16x16x32_bf16 v[46:49], v[134:137], v[200:203], v[46:49]
	v_mfma_f32_16x16x32_bf16 v[42:45], v[138:141], v[196:199], v[42:45]
	v_mfma_f32_16x16x32_bf16 v[42:45], v[142:145], v[200:203], v[42:45]
	v_mfma_f32_16x16x32_bf16 v[38:41], v[146:149], v[196:199], v[38:41]
	v_mfma_f32_16x16x32_bf16 v[38:41], v[150:153], v[200:203], v[38:41]
	v_mfma_f32_16x16x32_bf16 v[34:37], v[174:177], v[196:199], v[34:37]
	v_mfma_f32_16x16x32_bf16 v[34:37], v[178:181], v[200:203], v[34:37]
	v_mfma_f32_16x16x32_bf16 v[30:33], v[130:133], v[204:207], v[30:33]
	v_mfma_f32_16x16x32_bf16 v[30:33], v[134:137], v[208:211], v[30:33]
	v_mfma_f32_16x16x32_bf16 v[26:29], v[138:141], v[204:207], v[26:29]
	v_mfma_f32_16x16x32_bf16 v[26:29], v[142:145], v[208:211], v[26:29]
	v_mfma_f32_16x16x32_bf16 v[22:25], v[146:149], v[204:207], v[22:25]
	v_mfma_f32_16x16x32_bf16 v[22:25], v[150:153], v[208:211], v[22:25]
	v_mfma_f32_16x16x32_bf16 v[18:21], v[174:177], v[204:207], v[18:21]
	v_mfma_f32_16x16x32_bf16 v[18:21], v[178:181], v[208:211], v[18:21]
	v_mfma_f32_16x16x32_bf16 v[14:17], v[130:133], v[212:215], v[14:17]
	v_mfma_f32_16x16x32_bf16 v[14:17], v[134:137], v[216:219], v[14:17]
	v_mfma_f32_16x16x32_bf16 v[10:13], v[138:141], v[212:215], v[10:13]
	v_mfma_f32_16x16x32_bf16 v[10:13], v[142:145], v[216:219], v[10:13]
	v_mfma_f32_16x16x32_bf16 v[6:9], v[146:149], v[212:215], v[6:9]
	v_mfma_f32_16x16x32_bf16 v[6:9], v[150:153], v[216:219], v[6:9]
	v_mfma_f32_16x16x32_bf16 v[2:5], v[174:177], v[212:215], v[2:5]
	v_mfma_f32_16x16x32_bf16 v[2:5], v[178:181], v[216:219], v[2:5]
	s_barrier
	s_add_i32 s62, s62, 2
	s_add_u32 s26, s26, 0x100
	s_addc_u32 s27, s27, 0
	s_add_u32 s12, s12, 0x100
	s_addc_u32 s59, s59, 0
	s_cmpk_gt_u32 s62, 0xa9
	s_cbranch_scc0 .LBB0_2805
	s_setprio 0
	s_and_b64 vcc, exec, s[22:23]
	s_cbranch_vccz .LBB0_2808
	s_barrier
